# epilogues of ssm-branch / attn-merge / out-proj / ffn-out GEMMs: gate, residual and partial loads batched instead of serialized
# speedup vs baseline: 1.0106x; 1.0056x over previous
; __device__ __forceinline__ float bflo(unsigned u) { return __uint_as_float(u << 16); }
; __device__ __forceinline__ float bfhi(unsigned u) { return __uint_as_float(u & 0xffff0000u); }
; __device__ __forceinline__ float sigmoidf_(float x) { return __builtin_amdgcn_rcpf(1.f + __expf(-x)); }
; #define WIDE_STORE(BASE, LD, COFF, O) do { if ((m & 1) == 0) opend[n] = (O); \
;                 else *(uint4*)((BASE) + (size_t)tok * (LD) + (ncw - (COFF))) = swap_pair(opend[n], (O)); } while (0)
;     ...
;             for (int n = 0; n < 2; ++n) {
;               const int nc = brow + ai * 128 + wr * 64 + m * 16 + fq * 4;
;               const int tok = bcol + bj * 128 + wc * 32 + n * 16 + fr;
;               const int ncw = brow + ai * 128 + wr * 64 + ((m & ~1) + (fq & 1)) * 16 + (fq & ~1) * 4;
;     ...
;               f32x4 v = acc[ai][bj][m][n];
;               if (MODE == 0) {
;                 if (tn == 52) {
;                   if (ai == 0) *(float4*)((float*)(ws + OFF_DTR) + (size_t)tok * 128 + (nc - 13312)) = make_float4(v[0], v[1], v[2], v[3]);
;                 } else {
;                   u16* dst; int ld, c0;
;                   if (tn < 16) { dst = (u16*)(ws + OFF_Z); ld = 4096; c0 = 0; }
;                   else if (tn < 40) { dst = (u16*)(ws + OFF_RA); ld = 6144; c0 = 4096; }
;                   else if (tn < 48) { dst = (u16*)(ws + OFF_Q); ld = 2048; c0 = 10240; }
;                   else if (tn < 50) { dst = (u16*)(ws + OFF_K); ld = 512; c0 = 12288; }
;                   else { dst = (u16*)(ws + OFF_V); ld = 512; c0 = 12800; }
;                   uint2 o; o.x = pk2(v[0], v[1]); o.y = pk2(v[2], v[3]);
;                   WIDE_STORE(dst, ld, c0, o);
;                 }
;               } else if (MODE == 1) {
;                 uint2 o; o.x = pk2(sigmoidf_(v[0]), sigmoidf_(v[1])); o.y = pk2(sigmoidf_(v[2]), sigmoidf_(v[3]));
;                 WIDE_STORE((u16*)outp, 4096, 0, o);
;               } else if (MODE == 2) {
;                 const u16* gate = (const u16*)outp;
;                 uint2 ga = *(const uint2*)(gate + (size_t)tok * 4096 + nc);
;                 uint2 p1; p1.x = pk2(v[0] * bflo(ga.x), v[1] * bfhi(ga.x)); p1.y = pk2(v[2] * bflo(ga.y), v[3] * bfhi(ga.y));
;                 *(uint2*)((u16*)(ws + OFF_YB) + (size_t)tok * DM + nc) = p1;
.LBB0_813:
	v_readlane_b32 s2, v243, 57
	v_readlane_b32 s3, v243, 58
	v_readlane_b32 s4, v244, 3
	v_readlane_b32 s5, v244, 4
	s_add_i32 s0, s0, s49
	v_and_b32_e32 v172, 15, v146
	v_or_b32_e32 v172, s54, v172
	v_or_b32_e32 v172, s27, v172
	v_lshrrev_b32_e32 v173, 2, v146
	v_and_b32_e32 v174, -4, v173
	v_add_u32_e32 v174, s0, v174
	v_and_b32_e32 v173, -8, v173
	v_and_b32_e32 v175, 16, v146
	v_add3_u32 v173, v173, v175, s0
	v_lshlrev_b32_e32 v175, 13, v172
	v_lshl_add_u32 v134, v174, 1, v175
	v_add_u32_e32 v135, 0x20000, v134
	v_add_u32_e32 v136, 0x100000, v134
	v_add_u32_e32 v137, 0x120000, v134
	v_lshlrev_b32_e32 v175, 12, v172
	v_lshl_add_u32 v138, v174, 1, v175
	v_add_u32_e32 v139, 0x10000, v138
	v_add_u32_e32 v140, 0x80000, v138
	v_add_u32_e32 v141, 0x90000, v138
	global_load_dwordx2 v[210:211], v134, s[2:3] offset:0
	global_load_dwordx2 v[212:213], v134, s[2:3] offset:32
	global_load_dwordx2 v[214:215], v134, s[2:3] offset:64
	global_load_dwordx2 v[216:217], v134, s[2:3] offset:96
	global_load_dwordx2 v[218:219], v135, s[2:3] offset:0
	global_load_dwordx2 v[220:221], v135, s[2:3] offset:32
	global_load_dwordx2 v[222:223], v135, s[2:3] offset:64
	global_load_dwordx2 v[224:225], v135, s[2:3] offset:96
	global_load_dwordx2 v[226:227], v136, s[2:3] offset:0
	global_load_dwordx2 v[228:229], v136, s[2:3] offset:32
	global_load_dwordx2 v[230:231], v136, s[2:3] offset:64
	global_load_dwordx2 v[232:233], v136, s[2:3] offset:96
	global_load_dwordx2 v[234:235], v137, s[2:3] offset:0
	global_load_dwordx2 v[236:237], v137, s[2:3] offset:32
	global_load_dwordx2 v[238:239], v137, s[2:3] offset:64
	global_load_dwordx2 v[240:241], v137, s[2:3] offset:96
	s_waitcnt vmcnt(15)
	v_lshlrev_b32_e32 v168, 16, v210
	v_and_b32_e32 v169, 0xffff0000, v210
	v_lshlrev_b32_e32 v170, 16, v211
	v_and_b32_e32 v171, 0xffff0000, v211
	v_pk_mul_f32 v[124:125], v[124:125], v[168:169]
	v_pk_mul_f32 v[126:127], v[126:127], v[170:171]
	global_load_dwordx2 v[210:211], v134, s[2:3] offset:256
	s_waitcnt vmcnt(15)
	v_lshlrev_b32_e32 v168, 16, v212
	v_and_b32_e32 v169, 0xffff0000, v212
	v_lshlrev_b32_e32 v170, 16, v213
	v_and_b32_e32 v171, 0xffff0000, v213
	v_pk_mul_f32 v[116:117], v[116:117], v[168:169]
	v_pk_mul_f32 v[118:119], v[118:119], v[170:171]
	global_load_dwordx2 v[212:213], v134, s[2:3] offset:288
	s_waitcnt vmcnt(15)
	v_lshlrev_b32_e32 v168, 16, v214
	v_and_b32_e32 v169, 0xffff0000, v214
	v_lshlrev_b32_e32 v170, 16, v215
	v_and_b32_e32 v171, 0xffff0000, v215
	v_pk_mul_f32 v[108:109], v[108:109], v[168:169]
	v_pk_mul_f32 v[110:111], v[110:111], v[170:171]
	global_load_dwordx2 v[214:215], v134, s[2:3] offset:320
	s_waitcnt vmcnt(15)
	v_lshlrev_b32_e32 v168, 16, v216
	v_and_b32_e32 v169, 0xffff0000, v216
	v_lshlrev_b32_e32 v170, 16, v217
	v_and_b32_e32 v171, 0xffff0000, v217
	v_pk_mul_f32 v[100:101], v[100:101], v[168:169]
	v_pk_mul_f32 v[102:103], v[102:103], v[170:171]
	global_load_dwordx2 v[216:217], v134, s[2:3] offset:352
	s_nop 0
	v_cvt_pk_bf16_f32 v124, v124, v125
	v_cvt_pk_bf16_f32 v125, v126, v127
	v_cvt_pk_bf16_f32 v116, v116, v117
	v_cvt_pk_bf16_f32 v117, v118, v119
	v_cvt_pk_bf16_f32 v108, v108, v109
	v_cvt_pk_bf16_f32 v109, v110, v111
	v_cvt_pk_bf16_f32 v100, v100, v101
	v_cvt_pk_bf16_f32 v101, v102, v103
	global_store_dwordx2 v138, v[124:125], s[4:5] offset:0
	global_store_dwordx2 v138, v[116:117], s[4:5] offset:32
	global_store_dwordx2 v138, v[108:109], s[4:5] offset:64
	global_store_dwordx2 v138, v[100:101], s[4:5] offset:96
	s_waitcnt vmcnt(19)
	v_lshlrev_b32_e32 v168, 16, v218
	v_and_b32_e32 v169, 0xffff0000, v218
	v_lshlrev_b32_e32 v170, 16, v219
	v_and_b32_e32 v171, 0xffff0000, v219
	v_pk_mul_f32 v[120:121], v[120:121], v[168:169]
	v_pk_mul_f32 v[122:123], v[122:123], v[170:171]
	global_load_dwordx2 v[218:219], v135, s[2:3] offset:256
	s_waitcnt vmcnt(19)
	v_lshlrev_b32_e32 v168, 16, v220
	v_and_b32_e32 v169, 0xffff0000, v220
	v_lshlrev_b32_e32 v170, 16, v221
	v_and_b32_e32 v171, 0xffff0000, v221
	v_pk_mul_f32 v[112:113], v[112:113], v[168:169]
	v_pk_mul_f32 v[114:115], v[114:115], v[170:171]
	global_load_dwordx2 v[220:221], v135, s[2:3] offset:288
	s_waitcnt vmcnt(19)
	v_lshlrev_b32_e32 v168, 16, v222
	v_and_b32_e32 v169, 0xffff0000, v222
	v_lshlrev_b32_e32 v170, 16, v223
	v_and_b32_e32 v171, 0xffff0000, v223
	v_pk_mul_f32 v[104:105], v[104:105], v[168:169]
	v_pk_mul_f32 v[106:107], v[106:107], v[170:171]
	global_load_dwordx2 v[222:223], v135, s[2:3] offset:320
	s_waitcnt vmcnt(19)
	v_lshlrev_b32_e32 v168, 16, v224
	v_and_b32_e32 v169, 0xffff0000, v224
	v_lshlrev_b32_e32 v170, 16, v225
	v_and_b32_e32 v171, 0xffff0000, v225
	v_pk_mul_f32 v[96:97], v[96:97], v[168:169]
	v_pk_mul_f32 v[98:99], v[98:99], v[170:171]
	global_load_dwordx2 v[224:225], v135, s[2:3] offset:352
	s_nop 0
	v_cvt_pk_bf16_f32 v120, v120, v121
	v_cvt_pk_bf16_f32 v121, v122, v123
	v_cvt_pk_bf16_f32 v112, v112, v113
	v_cvt_pk_bf16_f32 v113, v114, v115
	v_cvt_pk_bf16_f32 v104, v104, v105
	v_cvt_pk_bf16_f32 v105, v106, v107
	v_cvt_pk_bf16_f32 v96, v96, v97
	v_cvt_pk_bf16_f32 v97, v98, v99
	global_store_dwordx2 v139, v[120:121], s[4:5] offset:0
	global_store_dwordx2 v139, v[112:113], s[4:5] offset:32
	global_store_dwordx2 v139, v[104:105], s[4:5] offset:64
	global_store_dwordx2 v139, v[96:97], s[4:5] offset:96
	s_waitcnt vmcnt(23)
	v_lshlrev_b32_e32 v168, 16, v226
	v_and_b32_e32 v169, 0xffff0000, v226
	v_lshlrev_b32_e32 v170, 16, v227
	v_and_b32_e32 v171, 0xffff0000, v227
	v_pk_mul_f32 v[92:93], v[92:93], v[168:169]
	v_pk_mul_f32 v[94:95], v[94:95], v[170:171]
	global_load_dwordx2 v[226:227], v136, s[2:3] offset:256
	s_waitcnt vmcnt(23)
; __device__ __forceinline__ float bflo(unsigned u) { return __uint_as_float(u << 16); }
; __device__ __forceinline__ float bfhi(unsigned u) { return __uint_as_float(u & 0xffff0000u); }
; __device__ __forceinline__ float sigmoidf_(float x) { return __builtin_amdgcn_rcpf(1.f + __expf(-x)); }
; #define WIDE_STORE(BASE, LD, COFF, O) do { if ((m & 1) == 0) opend[n] = (O); \
;                 else *(uint4*)((BASE) + (size_t)tok * (LD) + (ncw - (COFF))) = swap_pair(opend[n], (O)); } while (0)
;     ...
;             for (int n = 0; n < 2; ++n) {
;               const int nc = brow + ai * 128 + wr * 64 + m * 16 + fq * 4;
;               const int tok = bcol + bj * 128 + wc * 32 + n * 16 + fr;
;               const int ncw = brow + ai * 128 + wr * 64 + ((m & ~1) + (fq & 1)) * 16 + (fq & ~1) * 4;
;     ...
;               f32x4 v = acc[ai][bj][m][n];
;               if (MODE == 0) {
;                 if (tn == 52) {
;                   if (ai == 0) *(float4*)((float*)(ws + OFF_DTR) + (size_t)tok * 128 + (nc - 13312)) = make_float4(v[0], v[1], v[2], v[3]);
;                 } else {
;                   u16* dst; int ld, c0;
;                   if (tn < 16) { dst = (u16*)(ws + OFF_Z); ld = 4096; c0 = 0; }
;                   else if (tn < 40) { dst = (u16*)(ws + OFF_RA); ld = 6144; c0 = 4096; }
;                   else if (tn < 48) { dst = (u16*)(ws + OFF_Q); ld = 2048; c0 = 10240; }
;                   else if (tn < 50) { dst = (u16*)(ws + OFF_K); ld = 512; c0 = 12288; }
;                   else { dst = (u16*)(ws + OFF_V); ld = 512; c0 = 12800; }
;                   uint2 o; o.x = pk2(v[0], v[1]); o.y = pk2(v[2], v[3]);
;                   WIDE_STORE(dst, ld, c0, o);
;                 }
;               } else if (MODE == 1) {
;                 uint2 o; o.x = pk2(sigmoidf_(v[0]), sigmoidf_(v[1])); o.y = pk2(sigmoidf_(v[2]), sigmoidf_(v[3]));
;                 WIDE_STORE((u16*)outp, 4096, 0, o);
;               } else if (MODE == 2) {
;                 const u16* gate = (const u16*)outp;
;                 uint2 ga = *(const uint2*)(gate + (size_t)tok * 4096 + nc);
;                 uint2 p1; p1.x = pk2(v[0] * bflo(ga.x), v[1] * bfhi(ga.x)); p1.y = pk2(v[2] * bflo(ga.y), v[3] * bfhi(ga.y));
;                 *(uint2*)((u16*)(ws + OFF_YB) + (size_t)tok * DM + nc) = p1;
	v_lshlrev_b32_e32 v168, 16, v228
	v_and_b32_e32 v169, 0xffff0000, v228
	v_lshlrev_b32_e32 v170, 16, v229
	v_and_b32_e32 v171, 0xffff0000, v229
	v_pk_mul_f32 v[84:85], v[84:85], v[168:169]
	v_pk_mul_f32 v[86:87], v[86:87], v[170:171]
	global_load_dwordx2 v[228:229], v136, s[2:3] offset:288
	s_waitcnt vmcnt(23)
	v_lshlrev_b32_e32 v168, 16, v230
	v_and_b32_e32 v169, 0xffff0000, v230
	v_lshlrev_b32_e32 v170, 16, v231
	v_and_b32_e32 v171, 0xffff0000, v231
	v_pk_mul_f32 v[76:77], v[76:77], v[168:169]
	v_pk_mul_f32 v[78:79], v[78:79], v[170:171]
	global_load_dwordx2 v[230:231], v136, s[2:3] offset:320
	s_waitcnt vmcnt(23)
	v_lshlrev_b32_e32 v168, 16, v232
	v_and_b32_e32 v169, 0xffff0000, v232
	v_lshlrev_b32_e32 v170, 16, v233
	v_and_b32_e32 v171, 0xffff0000, v233
	v_pk_mul_f32 v[68:69], v[68:69], v[168:169]
	v_pk_mul_f32 v[70:71], v[70:71], v[170:171]
	global_load_dwordx2 v[232:233], v136, s[2:3] offset:352
	s_nop 0
	v_cvt_pk_bf16_f32 v92, v92, v93
	v_cvt_pk_bf16_f32 v93, v94, v95
	v_cvt_pk_bf16_f32 v84, v84, v85
	v_cvt_pk_bf16_f32 v85, v86, v87
	v_cvt_pk_bf16_f32 v76, v76, v77
	v_cvt_pk_bf16_f32 v77, v78, v79
	v_cvt_pk_bf16_f32 v68, v68, v69
	v_cvt_pk_bf16_f32 v69, v70, v71
	global_store_dwordx2 v140, v[92:93], s[4:5] offset:0
	global_store_dwordx2 v140, v[84:85], s[4:5] offset:32
	global_store_dwordx2 v140, v[76:77], s[4:5] offset:64
	global_store_dwordx2 v140, v[68:69], s[4:5] offset:96
	s_waitcnt vmcnt(27)
	v_lshlrev_b32_e32 v168, 16, v234
	v_and_b32_e32 v169, 0xffff0000, v234
	v_lshlrev_b32_e32 v170, 16, v235
	v_and_b32_e32 v171, 0xffff0000, v235
	v_pk_mul_f32 v[88:89], v[88:89], v[168:169]
	v_pk_mul_f32 v[90:91], v[90:91], v[170:171]
	global_load_dwordx2 v[234:235], v137, s[2:3] offset:256
	s_waitcnt vmcnt(27)
	v_lshlrev_b32_e32 v168, 16, v236
	v_and_b32_e32 v169, 0xffff0000, v236
	v_lshlrev_b32_e32 v170, 16, v237
	v_and_b32_e32 v171, 0xffff0000, v237
	v_pk_mul_f32 v[80:81], v[80:81], v[168:169]
	v_pk_mul_f32 v[82:83], v[82:83], v[170:171]
	global_load_dwordx2 v[236:237], v137, s[2:3] offset:288
	s_waitcnt vmcnt(27)
	v_lshlrev_b32_e32 v168, 16, v238
	v_and_b32_e32 v169, 0xffff0000, v238
	v_lshlrev_b32_e32 v170, 16, v239
	v_and_b32_e32 v171, 0xffff0000, v239
	v_pk_mul_f32 v[72:73], v[72:73], v[168:169]
	v_pk_mul_f32 v[74:75], v[74:75], v[170:171]
	global_load_dwordx2 v[238:239], v137, s[2:3] offset:320
	s_waitcnt vmcnt(27)
	v_lshlrev_b32_e32 v168, 16, v240
	v_and_b32_e32 v169, 0xffff0000, v240
	v_lshlrev_b32_e32 v170, 16, v241
	v_and_b32_e32 v171, 0xffff0000, v241
	v_pk_mul_f32 v[64:65], v[64:65], v[168:169]
	v_pk_mul_f32 v[66:67], v[66:67], v[170:171]
	global_load_dwordx2 v[240:241], v137, s[2:3] offset:352
	s_nop 0
	v_cvt_pk_bf16_f32 v88, v88, v89
	v_cvt_pk_bf16_f32 v89, v90, v91
	v_cvt_pk_bf16_f32 v80, v80, v81
	v_cvt_pk_bf16_f32 v81, v82, v83
	v_cvt_pk_bf16_f32 v72, v72, v73
	v_cvt_pk_bf16_f32 v73, v74, v75
	v_cvt_pk_bf16_f32 v64, v64, v65
	v_cvt_pk_bf16_f32 v65, v66, v67
	global_store_dwordx2 v141, v[88:89], s[4:5] offset:0
	global_store_dwordx2 v141, v[80:81], s[4:5] offset:32
	global_store_dwordx2 v141, v[72:73], s[4:5] offset:64
	global_store_dwordx2 v141, v[64:65], s[4:5] offset:96
	s_waitcnt vmcnt(31)
	v_lshlrev_b32_e32 v168, 16, v210
	v_and_b32_e32 v169, 0xffff0000, v210
	v_lshlrev_b32_e32 v170, 16, v211
	v_and_b32_e32 v171, 0xffff0000, v211
	v_pk_mul_f32 v[60:61], v[60:61], v[168:169]
	v_pk_mul_f32 v[62:63], v[62:63], v[170:171]
	s_waitcnt vmcnt(30)
	v_lshlrev_b32_e32 v168, 16, v212
	v_and_b32_e32 v169, 0xffff0000, v212
	v_lshlrev_b32_e32 v170, 16, v213
	v_and_b32_e32 v171, 0xffff0000, v213
	v_pk_mul_f32 v[52:53], v[52:53], v[168:169]
	v_pk_mul_f32 v[54:55], v[54:55], v[170:171]
	s_waitcnt vmcnt(29)
	v_lshlrev_b32_e32 v168, 16, v214
	v_and_b32_e32 v169, 0xffff0000, v214
	v_lshlrev_b32_e32 v170, 16, v215
	v_and_b32_e32 v171, 0xffff0000, v215
	v_pk_mul_f32 v[44:45], v[44:45], v[168:169]
	v_pk_mul_f32 v[46:47], v[46:47], v[170:171]
	s_waitcnt vmcnt(28)
	v_lshlrev_b32_e32 v168, 16, v216
	v_and_b32_e32 v169, 0xffff0000, v216
	v_lshlrev_b32_e32 v170, 16, v217
	v_and_b32_e32 v171, 0xffff0000, v217
	v_pk_mul_f32 v[36:37], v[36:37], v[168:169]
	v_pk_mul_f32 v[38:39], v[38:39], v[170:171]
	s_nop 0
	v_cvt_pk_bf16_f32 v60, v60, v61
	v_cvt_pk_bf16_f32 v61, v62, v63
	v_cvt_pk_bf16_f32 v52, v52, v53
	v_cvt_pk_bf16_f32 v53, v54, v55
	v_cvt_pk_bf16_f32 v44, v44, v45
	v_cvt_pk_bf16_f32 v45, v46, v47
	v_cvt_pk_bf16_f32 v36, v36, v37
	v_cvt_pk_bf16_f32 v37, v38, v39
	global_store_dwordx2 v138, v[60:61], s[4:5] offset:256
	global_store_dwordx2 v138, v[52:53], s[4:5] offset:288
	global_store_dwordx2 v138, v[44:45], s[4:5] offset:320
	global_store_dwordx2 v138, v[36:37], s[4:5] offset:352
	s_waitcnt vmcnt(27)
; __device__ __forceinline__ float bflo(unsigned u) { return __uint_as_float(u << 16); }
; __device__ __forceinline__ float bfhi(unsigned u) { return __uint_as_float(u & 0xffff0000u); }
; __device__ __forceinline__ float sigmoidf_(float x) { return __builtin_amdgcn_rcpf(1.f + __expf(-x)); }
; #define WIDE_STORE(BASE, LD, COFF, O) do { if ((m & 1) == 0) opend[n] = (O); \
;                 else *(uint4*)((BASE) + (size_t)tok * (LD) + (ncw - (COFF))) = swap_pair(opend[n], (O)); } while (0)
;     ...
;             for (int n = 0; n < 2; ++n) {
;               const int nc = brow + ai * 128 + wr * 64 + m * 16 + fq * 4;
;               const int tok = bcol + bj * 128 + wc * 32 + n * 16 + fr;
;               const int ncw = brow + ai * 128 + wr * 64 + ((m & ~1) + (fq & 1)) * 16 + (fq & ~1) * 4;
;     ...
;               f32x4 v = acc[ai][bj][m][n];
;               if (MODE == 0) {
;                 if (tn == 52) {
;                   if (ai == 0) *(float4*)((float*)(ws + OFF_DTR) + (size_t)tok * 128 + (nc - 13312)) = make_float4(v[0], v[1], v[2], v[3]);
;                 } else {
;                   u16* dst; int ld, c0;
;                   if (tn < 16) { dst = (u16*)(ws + OFF_Z); ld = 4096; c0 = 0; }
;                   else if (tn < 40) { dst = (u16*)(ws + OFF_RA); ld = 6144; c0 = 4096; }
;                   else if (tn < 48) { dst = (u16*)(ws + OFF_Q); ld = 2048; c0 = 10240; }
;                   else if (tn < 50) { dst = (u16*)(ws + OFF_K); ld = 512; c0 = 12288; }
;                   else { dst = (u16*)(ws + OFF_V); ld = 512; c0 = 12800; }
;                   uint2 o; o.x = pk2(v[0], v[1]); o.y = pk2(v[2], v[3]);
;                   WIDE_STORE(dst, ld, c0, o);
;                 }
;               } else if (MODE == 1) {
;                 uint2 o; o.x = pk2(sigmoidf_(v[0]), sigmoidf_(v[1])); o.y = pk2(sigmoidf_(v[2]), sigmoidf_(v[3]));
;                 WIDE_STORE((u16*)outp, 4096, 0, o);
;               } else if (MODE == 2) {
;                 const u16* gate = (const u16*)outp;
;                 uint2 ga = *(const uint2*)(gate + (size_t)tok * 4096 + nc);
;                 uint2 p1; p1.x = pk2(v[0] * bflo(ga.x), v[1] * bfhi(ga.x)); p1.y = pk2(v[2] * bflo(ga.y), v[3] * bfhi(ga.y));
;                 *(uint2*)((u16*)(ws + OFF_YB) + (size_t)tok * DM + nc) = p1;
	v_lshlrev_b32_e32 v168, 16, v218
	v_and_b32_e32 v169, 0xffff0000, v218
	v_lshlrev_b32_e32 v170, 16, v219
	v_and_b32_e32 v171, 0xffff0000, v219
	v_pk_mul_f32 v[56:57], v[56:57], v[168:169]
	v_pk_mul_f32 v[58:59], v[58:59], v[170:171]
	s_waitcnt vmcnt(26)
	v_lshlrev_b32_e32 v168, 16, v220
	v_and_b32_e32 v169, 0xffff0000, v220
	v_lshlrev_b32_e32 v170, 16, v221
	v_and_b32_e32 v171, 0xffff0000, v221
	v_pk_mul_f32 v[48:49], v[48:49], v[168:169]
	v_pk_mul_f32 v[50:51], v[50:51], v[170:171]
	s_waitcnt vmcnt(25)
	v_lshlrev_b32_e32 v168, 16, v222
	v_and_b32_e32 v169, 0xffff0000, v222
	v_lshlrev_b32_e32 v170, 16, v223
	v_and_b32_e32 v171, 0xffff0000, v223
	v_pk_mul_f32 v[40:41], v[40:41], v[168:169]
	v_pk_mul_f32 v[42:43], v[42:43], v[170:171]
	s_waitcnt vmcnt(24)
	v_lshlrev_b32_e32 v168, 16, v224
	v_and_b32_e32 v169, 0xffff0000, v224
	v_lshlrev_b32_e32 v170, 16, v225
	v_and_b32_e32 v171, 0xffff0000, v225
	v_pk_mul_f32 v[32:33], v[32:33], v[168:169]
	v_pk_mul_f32 v[34:35], v[34:35], v[170:171]
	s_nop 0
	v_cvt_pk_bf16_f32 v56, v56, v57
	v_cvt_pk_bf16_f32 v57, v58, v59
	v_cvt_pk_bf16_f32 v48, v48, v49
	v_cvt_pk_bf16_f32 v49, v50, v51
	v_cvt_pk_bf16_f32 v40, v40, v41
	v_cvt_pk_bf16_f32 v41, v42, v43
	v_cvt_pk_bf16_f32 v32, v32, v33
	v_cvt_pk_bf16_f32 v33, v34, v35
	global_store_dwordx2 v139, v[56:57], s[4:5] offset:256
	global_store_dwordx2 v139, v[48:49], s[4:5] offset:288
	global_store_dwordx2 v139, v[40:41], s[4:5] offset:320
	global_store_dwordx2 v139, v[32:33], s[4:5] offset:352
	s_waitcnt vmcnt(23)
	v_lshlrev_b32_e32 v168, 16, v226
	v_and_b32_e32 v169, 0xffff0000, v226
	v_lshlrev_b32_e32 v170, 16, v227
	v_and_b32_e32 v171, 0xffff0000, v227
	v_pk_mul_f32 v[28:29], v[28:29], v[168:169]
	v_pk_mul_f32 v[30:31], v[30:31], v[170:171]
	s_waitcnt vmcnt(22)
	v_lshlrev_b32_e32 v168, 16, v228
	v_and_b32_e32 v169, 0xffff0000, v228
	v_lshlrev_b32_e32 v170, 16, v229
	v_and_b32_e32 v171, 0xffff0000, v229
	v_pk_mul_f32 v[20:21], v[20:21], v[168:169]
	v_pk_mul_f32 v[22:23], v[22:23], v[170:171]
	s_waitcnt vmcnt(21)
	v_lshlrev_b32_e32 v168, 16, v230
	v_and_b32_e32 v169, 0xffff0000, v230
	v_lshlrev_b32_e32 v170, 16, v231
	v_and_b32_e32 v171, 0xffff0000, v231
	v_pk_mul_f32 v[12:13], v[12:13], v[168:169]
	v_pk_mul_f32 v[14:15], v[14:15], v[170:171]
	s_waitcnt vmcnt(20)
	v_lshlrev_b32_e32 v168, 16, v232
	v_and_b32_e32 v169, 0xffff0000, v232
	v_lshlrev_b32_e32 v170, 16, v233
	v_and_b32_e32 v171, 0xffff0000, v233
	v_pk_mul_f32 v[4:5], v[4:5], v[168:169]
	v_pk_mul_f32 v[6:7], v[6:7], v[170:171]
	s_nop 0
	v_cvt_pk_bf16_f32 v28, v28, v29
	v_cvt_pk_bf16_f32 v29, v30, v31
	v_cvt_pk_bf16_f32 v20, v20, v21
	v_cvt_pk_bf16_f32 v21, v22, v23
	v_cvt_pk_bf16_f32 v12, v12, v13
	v_cvt_pk_bf16_f32 v13, v14, v15
	v_cvt_pk_bf16_f32 v4, v4, v5
	v_cvt_pk_bf16_f32 v5, v6, v7
	global_store_dwordx2 v140, v[28:29], s[4:5] offset:256
	global_store_dwordx2 v140, v[20:21], s[4:5] offset:288
	global_store_dwordx2 v140, v[12:13], s[4:5] offset:320
	global_store_dwordx2 v140, v[4:5], s[4:5] offset:352
	s_waitcnt vmcnt(19)
	v_lshlrev_b32_e32 v168, 16, v234
	v_and_b32_e32 v169, 0xffff0000, v234
	v_lshlrev_b32_e32 v170, 16, v235
	v_and_b32_e32 v171, 0xffff0000, v235
	v_pk_mul_f32 v[24:25], v[24:25], v[168:169]
	v_pk_mul_f32 v[26:27], v[26:27], v[170:171]
	s_waitcnt vmcnt(18)
	v_lshlrev_b32_e32 v168, 16, v236
	v_and_b32_e32 v169, 0xffff0000, v236
	v_lshlrev_b32_e32 v170, 16, v237
	v_and_b32_e32 v171, 0xffff0000, v237
	v_pk_mul_f32 v[16:17], v[16:17], v[168:169]
	v_pk_mul_f32 v[18:19], v[18:19], v[170:171]
	s_waitcnt vmcnt(17)
	v_lshlrev_b32_e32 v168, 16, v238
	v_and_b32_e32 v169, 0xffff0000, v238
	v_lshlrev_b32_e32 v170, 16, v239
	v_and_b32_e32 v171, 0xffff0000, v239
	v_pk_mul_f32 v[8:9], v[8:9], v[168:169]
	v_pk_mul_f32 v[10:11], v[10:11], v[170:171]
	s_waitcnt vmcnt(16)
	v_lshlrev_b32_e32 v168, 16, v240
	v_and_b32_e32 v169, 0xffff0000, v240
	v_lshlrev_b32_e32 v170, 16, v241
	v_and_b32_e32 v171, 0xffff0000, v241
	v_pk_mul_f32 v[0:1], v[0:1], v[168:169]
	v_pk_mul_f32 v[2:3], v[2:3], v[170:171]
	s_nop 0
	v_cvt_pk_bf16_f32 v24, v24, v25
	v_cvt_pk_bf16_f32 v25, v26, v27
	v_cvt_pk_bf16_f32 v16, v16, v17
	v_cvt_pk_bf16_f32 v17, v18, v19
	v_cvt_pk_bf16_f32 v8, v8, v9
	v_cvt_pk_bf16_f32 v9, v10, v11
	v_cvt_pk_bf16_f32 v0, v0, v1
	v_cvt_pk_bf16_f32 v1, v2, v3
	global_store_dwordx2 v141, v[24:25], s[4:5] offset:256
	global_store_dwordx2 v141, v[16:17], s[4:5] offset:288
	global_store_dwordx2 v141, v[8:9], s[4:5] offset:320
	global_store_dwordx2 v141, v[0:1], s[4:5] offset:352
	s_and_b64 s[0:1], s[56:57], s[8:9]
	s_andn2_b64 vcc, exec, s[0:1]
	s_waitcnt vmcnt(0)
	s_cbranch_vccnz .LBB0_804
	s_barrier
	s_branch .LBB0_804

;     ...
;             for (int n = 0; n < 2; ++n) {
;               const int nc = brow + ai * 128 + wr * 64 + m * 16 + fq * 4;
;               const int tok = bcol + bj * 128 + wc * 32 + n * 16 + fr;
;               const int ncw = brow + ai * 128 + wr * 64 + ((m & ~1) + (fq & 1)) * 16 + (fq & ~1) * 4;
;     ...
;               f32x4 v = acc[ai][bj][m][n];
;               if (MODE == 0) {
;                 if (tn == 52) {
;                   if (ai == 0) *(float4*)((float*)(ws + OFF_DTR) + (size_t)tok * 128 + (nc - 13312)) = make_float4(v[0], v[1], v[2], v[3]);
;                 } else {
;                   u16* dst; int ld, c0;
;                   if (tn < 16) { dst = (u16*)(ws + OFF_Z); ld = 4096; c0 = 0; }
;                   else if (tn < 40) { dst = (u16*)(ws + OFF_RA); ld = 6144; c0 = 4096; }
;                   else if (tn < 48) { dst = (u16*)(ws + OFF_Q); ld = 2048; c0 = 10240; }
;                   else if (tn < 50) { dst = (u16*)(ws + OFF_K); ld = 512; c0 = 12288; }
;                   else { dst = (u16*)(ws + OFF_V); ld = 512; c0 = 12800; }
;                   uint2 o; o.x = pk2(v[0], v[1]); o.y = pk2(v[2], v[3]);
;                   WIDE_STORE(dst, ld, c0, o);
;                 }
;               } else if (MODE == 1) {
;                 uint2 o; o.x = pk2(sigmoidf_(v[0]), sigmoidf_(v[1])); o.y = pk2(sigmoidf_(v[2]), sigmoidf_(v[3]));
;                 WIDE_STORE((u16*)outp, 4096, 0, o);
;               } else if (MODE == 2) {
;                 const u16* gate = (const u16*)outp;
;                 uint2 ga = *(const uint2*)(gate + (size_t)tok * 4096 + nc);
;                 uint2 p1; p1.x = pk2(v[0] * bflo(ga.x), v[1] * bfhi(ga.x)); p1.y = pk2(v[2] * bflo(ga.y), v[3] * bfhi(ga.y));
;                 *(uint2*)((u16*)(ws + OFF_YB) + (size_t)tok * DM + nc) = p1;
;               } else if (MODE == 6) {
;                 const u16* gate = (const u16*)outp;
;                 uint2 gb = *(const uint2*)(gate + (size_t)tok * 4096 + 2048 + nc);
;                 const uint2 p1 = *(const uint2*)((const u16*)(ws + OFF_YB) + (size_t)tok * DM + nc);
;                 uint2 o;
;                 o.x = pk2(bflo(p1.x) + v[0] * bflo(gb.x), bfhi(p1.x) + v[1] * bfhi(gb.x));
;                 o.y = pk2(bflo(p1.y) + v[2] * bflo(gb.y), bfhi(p1.y) + v[3] * bfhi(gb.y));
;                 WIDE_STORE((u16*)(ws + OFF_RB + 128 * MiB), DM, 0, o);
.LBB0_828:
	v_readlane_b32 s28, v243, 57
	v_readlane_b32 s29, v243, 58
	v_readlane_b32 s4, v244, 3
	v_readlane_b32 s5, v244, 4
	s_add_i32 s0, s0, s49
	v_and_b32_e32 v172, 15, v158
	v_or_b32_e32 v172, s54, v172
	v_or_b32_e32 v172, s27, v172
	v_lshrrev_b32_e32 v173, 2, v158
	v_and_b32_e32 v174, -4, v173
	v_add_u32_e32 v174, s0, v174
	v_and_b32_e32 v173, -8, v173
	v_and_b32_e32 v175, 16, v158
	v_add3_u32 v173, v173, v175, s0
	v_lshlrev_b32_e32 v175, 13, v172
	v_lshl_add_u32 v134, v174, 1, v175
	v_add_u32_e32 v134, 0x1000, v134
	v_add_u32_e32 v135, 0x20000, v134
	v_add_u32_e32 v136, 0x100000, v134
	v_add_u32_e32 v137, 0x120000, v134
	v_lshlrev_b32_e32 v175, 12, v172
	v_lshl_add_u32 v138, v174, 1, v175
	v_add_u32_e32 v139, 0x10000, v138
	v_add_u32_e32 v140, 0x80000, v138
	v_add_u32_e32 v141, 0x90000, v138
	v_lshlrev_b32_e32 v175, 12, v172
	v_lshl_add_u32 v190, v173, 1, v175
	v_add_u32_e32 v191, 0x10000, v190
	v_add_u32_e32 v192, 0x80000, v190
	v_add_u32_e32 v193, 0x90000, v190
	global_load_dwordx2 v[210:211], v134, s[28:29] offset:0
	global_load_dwordx2 v[212:213], v138, s[4:5] offset:0
	global_load_dwordx2 v[214:215], v134, s[28:29] offset:32
	global_load_dwordx2 v[216:217], v138, s[4:5] offset:32
	global_load_dwordx2 v[218:219], v134, s[28:29] offset:64
	global_load_dwordx2 v[220:221], v138, s[4:5] offset:64
	global_load_dwordx2 v[222:223], v134, s[28:29] offset:96
	global_load_dwordx2 v[224:225], v138, s[4:5] offset:96
	global_load_dwordx2 v[226:227], v135, s[28:29] offset:0
	global_load_dwordx2 v[228:229], v139, s[4:5] offset:0
	global_load_dwordx2 v[230:231], v135, s[28:29] offset:32
	global_load_dwordx2 v[232:233], v139, s[4:5] offset:32
	global_load_dwordx2 v[234:235], v135, s[28:29] offset:64
	global_load_dwordx2 v[236:237], v139, s[4:5] offset:64
	global_load_dwordx2 v[238:239], v135, s[28:29] offset:96
	global_load_dwordx2 v[240:241], v139, s[4:5] offset:96
	s_waitcnt vmcnt(14)
	v_lshlrev_b32_e32 v168, 16, v210
	v_and_b32_e32 v169, 0xffff0000, v210
	v_lshlrev_b32_e32 v176, 16, v212
	v_and_b32_e32 v177, 0xffff0000, v212
	v_pk_fma_f32 v[124:125], v[124:125], v[168:169], v[176:177]
	v_lshlrev_b32_e32 v170, 16, v211
	v_and_b32_e32 v171, 0xffff0000, v211
	v_lshlrev_b32_e32 v178, 16, v213
	v_and_b32_e32 v179, 0xffff0000, v213
	v_pk_fma_f32 v[126:127], v[126:127], v[170:171], v[178:179]
	global_load_dwordx2 v[210:211], v136, s[28:29] offset:0
	global_load_dwordx2 v[212:213], v140, s[4:5] offset:0
	s_waitcnt vmcnt(14)
	v_lshlrev_b32_e32 v168, 16, v214
	v_and_b32_e32 v169, 0xffff0000, v214
	v_lshlrev_b32_e32 v176, 16, v216
	v_and_b32_e32 v177, 0xffff0000, v216
	v_pk_fma_f32 v[116:117], v[116:117], v[168:169], v[176:177]
	v_lshlrev_b32_e32 v170, 16, v215
	v_and_b32_e32 v171, 0xffff0000, v215
	v_lshlrev_b32_e32 v178, 16, v217
	v_and_b32_e32 v179, 0xffff0000, v217
	v_pk_fma_f32 v[118:119], v[118:119], v[170:171], v[178:179]
	global_load_dwordx2 v[214:215], v136, s[28:29] offset:32
	global_load_dwordx2 v[216:217], v140, s[4:5] offset:32
	s_waitcnt vmcnt(14)
	v_lshlrev_b32_e32 v168, 16, v218
	v_and_b32_e32 v169, 0xffff0000, v218
	v_lshlrev_b32_e32 v176, 16, v220
	v_and_b32_e32 v177, 0xffff0000, v220
	v_pk_fma_f32 v[108:109], v[108:109], v[168:169], v[176:177]
	v_lshlrev_b32_e32 v170, 16, v219
	v_and_b32_e32 v171, 0xffff0000, v219
	v_lshlrev_b32_e32 v178, 16, v221
	v_and_b32_e32 v179, 0xffff0000, v221
	v_pk_fma_f32 v[110:111], v[110:111], v[170:171], v[178:179]
	global_load_dwordx2 v[218:219], v136, s[28:29] offset:64
	global_load_dwordx2 v[220:221], v140, s[4:5] offset:64
	s_waitcnt vmcnt(14)
	v_lshlrev_b32_e32 v168, 16, v222
	v_and_b32_e32 v169, 0xffff0000, v222
	v_lshlrev_b32_e32 v176, 16, v224
	v_and_b32_e32 v177, 0xffff0000, v224
	v_pk_fma_f32 v[100:101], v[100:101], v[168:169], v[176:177]
	v_lshlrev_b32_e32 v170, 16, v223
	v_and_b32_e32 v171, 0xffff0000, v223
	v_lshlrev_b32_e32 v178, 16, v225
	v_and_b32_e32 v179, 0xffff0000, v225
	v_pk_fma_f32 v[102:103], v[102:103], v[170:171], v[178:179]
	global_load_dwordx2 v[222:223], v136, s[28:29] offset:96
	global_load_dwordx2 v[224:225], v140, s[4:5] offset:96
	s_nop 0
	v_cvt_pk_bf16_f32 v124, v124, v125
	v_cvt_pk_bf16_f32 v125, v126, v127
	v_cvt_pk_bf16_f32 v126, v116, v117
	v_cvt_pk_bf16_f32 v127, v118, v119
	v_cvt_pk_bf16_f32 v108, v108, v109
	v_cvt_pk_bf16_f32 v109, v110, v111
	v_cvt_pk_bf16_f32 v110, v100, v101
	v_cvt_pk_bf16_f32 v111, v102, v103
	s_nop 1
	v_permlane16_swap_b32_e32 v124, v126
	v_permlane16_swap_b32_e32 v125, v127
	v_permlane16_swap_b32_e32 v108, v110
	v_permlane16_swap_b32_e32 v109, v111
	global_store_dwordx4 v190, v[124:127], s[72:73] offset:0
	global_store_dwordx4 v190, v[108:111], s[72:73] offset:64
	s_waitcnt vmcnt(16)
	v_lshlrev_b32_e32 v168, 16, v226
	v_and_b32_e32 v169, 0xffff0000, v226
	v_lshlrev_b32_e32 v176, 16, v228
	v_and_b32_e32 v177, 0xffff0000, v228
	v_pk_fma_f32 v[120:121], v[120:121], v[168:169], v[176:177]
	v_lshlrev_b32_e32 v170, 16, v227
	v_and_b32_e32 v171, 0xffff0000, v227
	v_lshlrev_b32_e32 v178, 16, v229
	v_and_b32_e32 v179, 0xffff0000, v229
	v_pk_fma_f32 v[122:123], v[122:123], v[170:171], v[178:179]
	global_load_dwordx2 v[226:227], v137, s[28:29] offset:0
	global_load_dwordx2 v[228:229], v141, s[4:5] offset:0
	s_waitcnt vmcnt(16)
	v_lshlrev_b32_e32 v168, 16, v230
	v_and_b32_e32 v169, 0xffff0000, v230
	v_lshlrev_b32_e32 v176, 16, v232
	v_and_b32_e32 v177, 0xffff0000, v232
	v_pk_fma_f32 v[112:113], v[112:113], v[168:169], v[176:177]
	v_lshlrev_b32_e32 v170, 16, v231
	v_and_b32_e32 v171, 0xffff0000, v231
	v_lshlrev_b32_e32 v178, 16, v233
	v_and_b32_e32 v179, 0xffff0000, v233
	v_pk_fma_f32 v[114:115], v[114:115], v[170:171], v[178:179]
	global_load_dwordx2 v[230:231], v137, s[28:29] offset:32
	global_load_dwordx2 v[232:233], v141, s[4:5] offset:32
	s_waitcnt vmcnt(16)
;     ...
;             for (int n = 0; n < 2; ++n) {
;               const int nc = brow + ai * 128 + wr * 64 + m * 16 + fq * 4;
;               const int tok = bcol + bj * 128 + wc * 32 + n * 16 + fr;
;               const int ncw = brow + ai * 128 + wr * 64 + ((m & ~1) + (fq & 1)) * 16 + (fq & ~1) * 4;
;     ...
;               f32x4 v = acc[ai][bj][m][n];
;               if (MODE == 0) {
;                 if (tn == 52) {
;                   if (ai == 0) *(float4*)((float*)(ws + OFF_DTR) + (size_t)tok * 128 + (nc - 13312)) = make_float4(v[0], v[1], v[2], v[3]);
;                 } else {
;                   u16* dst; int ld, c0;
;                   if (tn < 16) { dst = (u16*)(ws + OFF_Z); ld = 4096; c0 = 0; }
;                   else if (tn < 40) { dst = (u16*)(ws + OFF_RA); ld = 6144; c0 = 4096; }
;                   else if (tn < 48) { dst = (u16*)(ws + OFF_Q); ld = 2048; c0 = 10240; }
;                   else if (tn < 50) { dst = (u16*)(ws + OFF_K); ld = 512; c0 = 12288; }
;                   else { dst = (u16*)(ws + OFF_V); ld = 512; c0 = 12800; }
;                   uint2 o; o.x = pk2(v[0], v[1]); o.y = pk2(v[2], v[3]);
;                   WIDE_STORE(dst, ld, c0, o);
;                 }
;               } else if (MODE == 1) {
;                 uint2 o; o.x = pk2(sigmoidf_(v[0]), sigmoidf_(v[1])); o.y = pk2(sigmoidf_(v[2]), sigmoidf_(v[3]));
;                 WIDE_STORE((u16*)outp, 4096, 0, o);
;               } else if (MODE == 2) {
;                 const u16* gate = (const u16*)outp;
;                 uint2 ga = *(const uint2*)(gate + (size_t)tok * 4096 + nc);
;                 uint2 p1; p1.x = pk2(v[0] * bflo(ga.x), v[1] * bfhi(ga.x)); p1.y = pk2(v[2] * bflo(ga.y), v[3] * bfhi(ga.y));
;                 *(uint2*)((u16*)(ws + OFF_YB) + (size_t)tok * DM + nc) = p1;
;               } else if (MODE == 6) {
;                 const u16* gate = (const u16*)outp;
;                 uint2 gb = *(const uint2*)(gate + (size_t)tok * 4096 + 2048 + nc);
;                 const uint2 p1 = *(const uint2*)((const u16*)(ws + OFF_YB) + (size_t)tok * DM + nc);
;                 uint2 o;
;                 o.x = pk2(bflo(p1.x) + v[0] * bflo(gb.x), bfhi(p1.x) + v[1] * bfhi(gb.x));
;                 o.y = pk2(bflo(p1.y) + v[2] * bflo(gb.y), bfhi(p1.y) + v[3] * bfhi(gb.y));
;                 WIDE_STORE((u16*)(ws + OFF_RB + 128 * MiB), DM, 0, o);
	v_lshlrev_b32_e32 v168, 16, v234
	v_and_b32_e32 v169, 0xffff0000, v234
	v_lshlrev_b32_e32 v176, 16, v236
	v_and_b32_e32 v177, 0xffff0000, v236
	v_pk_fma_f32 v[104:105], v[104:105], v[168:169], v[176:177]
	v_lshlrev_b32_e32 v170, 16, v235
	v_and_b32_e32 v171, 0xffff0000, v235
	v_lshlrev_b32_e32 v178, 16, v237
	v_and_b32_e32 v179, 0xffff0000, v237
	v_pk_fma_f32 v[106:107], v[106:107], v[170:171], v[178:179]
	global_load_dwordx2 v[234:235], v137, s[28:29] offset:64
	global_load_dwordx2 v[236:237], v141, s[4:5] offset:64
	s_waitcnt vmcnt(16)
	v_lshlrev_b32_e32 v168, 16, v238
	v_and_b32_e32 v169, 0xffff0000, v238
	v_lshlrev_b32_e32 v176, 16, v240
	v_and_b32_e32 v177, 0xffff0000, v240
	v_pk_fma_f32 v[96:97], v[96:97], v[168:169], v[176:177]
	v_lshlrev_b32_e32 v170, 16, v239
	v_and_b32_e32 v171, 0xffff0000, v239
	v_lshlrev_b32_e32 v178, 16, v241
	v_and_b32_e32 v179, 0xffff0000, v241
	v_pk_fma_f32 v[98:99], v[98:99], v[170:171], v[178:179]
	global_load_dwordx2 v[238:239], v137, s[28:29] offset:96
	global_load_dwordx2 v[240:241], v141, s[4:5] offset:96
	s_nop 0
	v_cvt_pk_bf16_f32 v120, v120, v121
	v_cvt_pk_bf16_f32 v121, v122, v123
	v_cvt_pk_bf16_f32 v122, v112, v113
	v_cvt_pk_bf16_f32 v123, v114, v115
	v_cvt_pk_bf16_f32 v104, v104, v105
	v_cvt_pk_bf16_f32 v105, v106, v107
	v_cvt_pk_bf16_f32 v106, v96, v97
	v_cvt_pk_bf16_f32 v107, v98, v99
	s_nop 1
	v_permlane16_swap_b32_e32 v120, v122
	v_permlane16_swap_b32_e32 v121, v123
	v_permlane16_swap_b32_e32 v104, v106
	v_permlane16_swap_b32_e32 v105, v107
	global_store_dwordx4 v191, v[120:123], s[72:73] offset:0
	global_store_dwordx4 v191, v[104:107], s[72:73] offset:64
	s_waitcnt vmcnt(18)
	v_lshlrev_b32_e32 v168, 16, v210
	v_and_b32_e32 v169, 0xffff0000, v210
	v_lshlrev_b32_e32 v176, 16, v212
	v_and_b32_e32 v177, 0xffff0000, v212
	v_pk_fma_f32 v[92:93], v[92:93], v[168:169], v[176:177]
	v_lshlrev_b32_e32 v170, 16, v211
	v_and_b32_e32 v171, 0xffff0000, v211
	v_lshlrev_b32_e32 v178, 16, v213
	v_and_b32_e32 v179, 0xffff0000, v213
	v_pk_fma_f32 v[94:95], v[94:95], v[170:171], v[178:179]
	global_load_dwordx2 v[210:211], v134, s[28:29] offset:256
	global_load_dwordx2 v[212:213], v138, s[4:5] offset:256
	s_waitcnt vmcnt(18)
	v_lshlrev_b32_e32 v168, 16, v214
	v_and_b32_e32 v169, 0xffff0000, v214
	v_lshlrev_b32_e32 v176, 16, v216
	v_and_b32_e32 v177, 0xffff0000, v216
	v_pk_fma_f32 v[84:85], v[84:85], v[168:169], v[176:177]
	v_lshlrev_b32_e32 v170, 16, v215
	v_and_b32_e32 v171, 0xffff0000, v215
	v_lshlrev_b32_e32 v178, 16, v217
	v_and_b32_e32 v179, 0xffff0000, v217
	v_pk_fma_f32 v[86:87], v[86:87], v[170:171], v[178:179]
	global_load_dwordx2 v[214:215], v134, s[28:29] offset:288
	global_load_dwordx2 v[216:217], v138, s[4:5] offset:288
	s_waitcnt vmcnt(18)
	v_lshlrev_b32_e32 v168, 16, v218
	v_and_b32_e32 v169, 0xffff0000, v218
	v_lshlrev_b32_e32 v176, 16, v220
	v_and_b32_e32 v177, 0xffff0000, v220
	v_pk_fma_f32 v[76:77], v[76:77], v[168:169], v[176:177]
	v_lshlrev_b32_e32 v170, 16, v219
	v_and_b32_e32 v171, 0xffff0000, v219
	v_lshlrev_b32_e32 v178, 16, v221
	v_and_b32_e32 v179, 0xffff0000, v221
	v_pk_fma_f32 v[78:79], v[78:79], v[170:171], v[178:179]
	global_load_dwordx2 v[218:219], v134, s[28:29] offset:320
	global_load_dwordx2 v[220:221], v138, s[4:5] offset:320
	s_waitcnt vmcnt(18)
	v_lshlrev_b32_e32 v168, 16, v222
	v_and_b32_e32 v169, 0xffff0000, v222
	v_lshlrev_b32_e32 v176, 16, v224
	v_and_b32_e32 v177, 0xffff0000, v224
	v_pk_fma_f32 v[68:69], v[68:69], v[168:169], v[176:177]
	v_lshlrev_b32_e32 v170, 16, v223
	v_and_b32_e32 v171, 0xffff0000, v223
	v_lshlrev_b32_e32 v178, 16, v225
	v_and_b32_e32 v179, 0xffff0000, v225
	v_pk_fma_f32 v[70:71], v[70:71], v[170:171], v[178:179]
	global_load_dwordx2 v[222:223], v134, s[28:29] offset:352
	global_load_dwordx2 v[224:225], v138, s[4:5] offset:352
	s_nop 0
	v_cvt_pk_bf16_f32 v92, v92, v93
	v_cvt_pk_bf16_f32 v93, v94, v95
	v_cvt_pk_bf16_f32 v94, v84, v85
	v_cvt_pk_bf16_f32 v95, v86, v87
	v_cvt_pk_bf16_f32 v76, v76, v77
	v_cvt_pk_bf16_f32 v77, v78, v79
	v_cvt_pk_bf16_f32 v78, v68, v69
	v_cvt_pk_bf16_f32 v79, v70, v71
	s_nop 1
	v_permlane16_swap_b32_e32 v92, v94
	v_permlane16_swap_b32_e32 v93, v95
	v_permlane16_swap_b32_e32 v76, v78
	v_permlane16_swap_b32_e32 v77, v79
	global_store_dwordx4 v192, v[92:95], s[72:73] offset:0
	global_store_dwordx4 v192, v[76:79], s[72:73] offset:64
	s_waitcnt vmcnt(18)
	v_lshlrev_b32_e32 v168, 16, v226
	v_and_b32_e32 v169, 0xffff0000, v226
	v_lshlrev_b32_e32 v176, 16, v228
	v_and_b32_e32 v177, 0xffff0000, v228
	v_pk_fma_f32 v[88:89], v[88:89], v[168:169], v[176:177]
	v_lshlrev_b32_e32 v170, 16, v227
	v_and_b32_e32 v171, 0xffff0000, v227
	v_lshlrev_b32_e32 v178, 16, v229
	v_and_b32_e32 v179, 0xffff0000, v229
	v_pk_fma_f32 v[90:91], v[90:91], v[170:171], v[178:179]
	global_load_dwordx2 v[226:227], v135, s[28:29] offset:256
	global_load_dwordx2 v[228:229], v139, s[4:5] offset:256
	s_waitcnt vmcnt(18)
	v_lshlrev_b32_e32 v168, 16, v230
	v_and_b32_e32 v169, 0xffff0000, v230
	v_lshlrev_b32_e32 v176, 16, v232
	v_and_b32_e32 v177, 0xffff0000, v232
	v_pk_fma_f32 v[80:81], v[80:81], v[168:169], v[176:177]
	v_lshlrev_b32_e32 v170, 16, v231
	v_and_b32_e32 v171, 0xffff0000, v231
	v_lshlrev_b32_e32 v178, 16, v233
	v_and_b32_e32 v179, 0xffff0000, v233
	v_pk_fma_f32 v[82:83], v[82:83], v[170:171], v[178:179]
	global_load_dwordx2 v[230:231], v135, s[28:29] offset:288
	global_load_dwordx2 v[232:233], v139, s[4:5] offset:288
	s_waitcnt vmcnt(18)
;     ...
;             for (int n = 0; n < 2; ++n) {
;               const int nc = brow + ai * 128 + wr * 64 + m * 16 + fq * 4;
;               const int tok = bcol + bj * 128 + wc * 32 + n * 16 + fr;
;               const int ncw = brow + ai * 128 + wr * 64 + ((m & ~1) + (fq & 1)) * 16 + (fq & ~1) * 4;
;     ...
;               f32x4 v = acc[ai][bj][m][n];
;               if (MODE == 0) {
;                 if (tn == 52) {
;                   if (ai == 0) *(float4*)((float*)(ws + OFF_DTR) + (size_t)tok * 128 + (nc - 13312)) = make_float4(v[0], v[1], v[2], v[3]);
;                 } else {
;                   u16* dst; int ld, c0;
;                   if (tn < 16) { dst = (u16*)(ws + OFF_Z); ld = 4096; c0 = 0; }
;                   else if (tn < 40) { dst = (u16*)(ws + OFF_RA); ld = 6144; c0 = 4096; }
;                   else if (tn < 48) { dst = (u16*)(ws + OFF_Q); ld = 2048; c0 = 10240; }
;                   else if (tn < 50) { dst = (u16*)(ws + OFF_K); ld = 512; c0 = 12288; }
;                   else { dst = (u16*)(ws + OFF_V); ld = 512; c0 = 12800; }
;                   uint2 o; o.x = pk2(v[0], v[1]); o.y = pk2(v[2], v[3]);
;                   WIDE_STORE(dst, ld, c0, o);
;                 }
;               } else if (MODE == 1) {
;                 uint2 o; o.x = pk2(sigmoidf_(v[0]), sigmoidf_(v[1])); o.y = pk2(sigmoidf_(v[2]), sigmoidf_(v[3]));
;                 WIDE_STORE((u16*)outp, 4096, 0, o);
;               } else if (MODE == 2) {
;                 const u16* gate = (const u16*)outp;
;                 uint2 ga = *(const uint2*)(gate + (size_t)tok * 4096 + nc);
;                 uint2 p1; p1.x = pk2(v[0] * bflo(ga.x), v[1] * bfhi(ga.x)); p1.y = pk2(v[2] * bflo(ga.y), v[3] * bfhi(ga.y));
;                 *(uint2*)((u16*)(ws + OFF_YB) + (size_t)tok * DM + nc) = p1;
;               } else if (MODE == 6) {
;                 const u16* gate = (const u16*)outp;
;                 uint2 gb = *(const uint2*)(gate + (size_t)tok * 4096 + 2048 + nc);
;                 const uint2 p1 = *(const uint2*)((const u16*)(ws + OFF_YB) + (size_t)tok * DM + nc);
;                 uint2 o;
;                 o.x = pk2(bflo(p1.x) + v[0] * bflo(gb.x), bfhi(p1.x) + v[1] * bfhi(gb.x));
;                 o.y = pk2(bflo(p1.y) + v[2] * bflo(gb.y), bfhi(p1.y) + v[3] * bfhi(gb.y));
;                 WIDE_STORE((u16*)(ws + OFF_RB + 128 * MiB), DM, 0, o);
	v_lshlrev_b32_e32 v168, 16, v234
	v_and_b32_e32 v169, 0xffff0000, v234
	v_lshlrev_b32_e32 v176, 16, v236
	v_and_b32_e32 v177, 0xffff0000, v236
	v_pk_fma_f32 v[72:73], v[72:73], v[168:169], v[176:177]
	v_lshlrev_b32_e32 v170, 16, v235
	v_and_b32_e32 v171, 0xffff0000, v235
	v_lshlrev_b32_e32 v178, 16, v237
	v_and_b32_e32 v179, 0xffff0000, v237
	v_pk_fma_f32 v[74:75], v[74:75], v[170:171], v[178:179]
	global_load_dwordx2 v[234:235], v135, s[28:29] offset:320
	global_load_dwordx2 v[236:237], v139, s[4:5] offset:320
	s_waitcnt vmcnt(18)
	v_lshlrev_b32_e32 v168, 16, v238
	v_and_b32_e32 v169, 0xffff0000, v238
	v_lshlrev_b32_e32 v176, 16, v240
	v_and_b32_e32 v177, 0xffff0000, v240
	v_pk_fma_f32 v[64:65], v[64:65], v[168:169], v[176:177]
	v_lshlrev_b32_e32 v170, 16, v239
	v_and_b32_e32 v171, 0xffff0000, v239
	v_lshlrev_b32_e32 v178, 16, v241
	v_and_b32_e32 v179, 0xffff0000, v241
	v_pk_fma_f32 v[66:67], v[66:67], v[170:171], v[178:179]
	global_load_dwordx2 v[238:239], v135, s[28:29] offset:352
	global_load_dwordx2 v[240:241], v139, s[4:5] offset:352
	s_nop 0
	v_cvt_pk_bf16_f32 v88, v88, v89
	v_cvt_pk_bf16_f32 v89, v90, v91
	v_cvt_pk_bf16_f32 v90, v80, v81
	v_cvt_pk_bf16_f32 v91, v82, v83
	v_cvt_pk_bf16_f32 v72, v72, v73
	v_cvt_pk_bf16_f32 v73, v74, v75
	v_cvt_pk_bf16_f32 v74, v64, v65
	v_cvt_pk_bf16_f32 v75, v66, v67
	s_nop 1
	v_permlane16_swap_b32_e32 v88, v90
	v_permlane16_swap_b32_e32 v89, v91
	v_permlane16_swap_b32_e32 v72, v74
	v_permlane16_swap_b32_e32 v73, v75
	global_store_dwordx4 v193, v[88:91], s[72:73] offset:0
	global_store_dwordx4 v193, v[72:75], s[72:73] offset:64
	s_waitcnt vmcnt(18)
	v_lshlrev_b32_e32 v168, 16, v210
	v_and_b32_e32 v169, 0xffff0000, v210
	v_lshlrev_b32_e32 v176, 16, v212
	v_and_b32_e32 v177, 0xffff0000, v212
	v_pk_fma_f32 v[60:61], v[60:61], v[168:169], v[176:177]
	v_lshlrev_b32_e32 v170, 16, v211
	v_and_b32_e32 v171, 0xffff0000, v211
	v_lshlrev_b32_e32 v178, 16, v213
	v_and_b32_e32 v179, 0xffff0000, v213
	v_pk_fma_f32 v[62:63], v[62:63], v[170:171], v[178:179]
	global_load_dwordx2 v[210:211], v136, s[28:29] offset:256
	global_load_dwordx2 v[212:213], v140, s[4:5] offset:256
	s_waitcnt vmcnt(18)
	v_lshlrev_b32_e32 v168, 16, v214
	v_and_b32_e32 v169, 0xffff0000, v214
	v_lshlrev_b32_e32 v176, 16, v216
	v_and_b32_e32 v177, 0xffff0000, v216
	v_pk_fma_f32 v[52:53], v[52:53], v[168:169], v[176:177]
	v_lshlrev_b32_e32 v170, 16, v215
	v_and_b32_e32 v171, 0xffff0000, v215
	v_lshlrev_b32_e32 v178, 16, v217
	v_and_b32_e32 v179, 0xffff0000, v217
	v_pk_fma_f32 v[54:55], v[54:55], v[170:171], v[178:179]
	global_load_dwordx2 v[214:215], v136, s[28:29] offset:288
	global_load_dwordx2 v[216:217], v140, s[4:5] offset:288
	s_waitcnt vmcnt(18)
	v_lshlrev_b32_e32 v168, 16, v218
	v_and_b32_e32 v169, 0xffff0000, v218
	v_lshlrev_b32_e32 v176, 16, v220
	v_and_b32_e32 v177, 0xffff0000, v220
	v_pk_fma_f32 v[44:45], v[44:45], v[168:169], v[176:177]
	v_lshlrev_b32_e32 v170, 16, v219
	v_and_b32_e32 v171, 0xffff0000, v219
	v_lshlrev_b32_e32 v178, 16, v221
	v_and_b32_e32 v179, 0xffff0000, v221
	v_pk_fma_f32 v[46:47], v[46:47], v[170:171], v[178:179]
	global_load_dwordx2 v[218:219], v136, s[28:29] offset:320
	global_load_dwordx2 v[220:221], v140, s[4:5] offset:320
	s_waitcnt vmcnt(18)
	v_lshlrev_b32_e32 v168, 16, v222
	v_and_b32_e32 v169, 0xffff0000, v222
	v_lshlrev_b32_e32 v176, 16, v224
	v_and_b32_e32 v177, 0xffff0000, v224
	v_pk_fma_f32 v[36:37], v[36:37], v[168:169], v[176:177]
	v_lshlrev_b32_e32 v170, 16, v223
	v_and_b32_e32 v171, 0xffff0000, v223
	v_lshlrev_b32_e32 v178, 16, v225
	v_and_b32_e32 v179, 0xffff0000, v225
	v_pk_fma_f32 v[38:39], v[38:39], v[170:171], v[178:179]
	global_load_dwordx2 v[222:223], v136, s[28:29] offset:352
	global_load_dwordx2 v[224:225], v140, s[4:5] offset:352
	s_nop 0
	v_cvt_pk_bf16_f32 v60, v60, v61
	v_cvt_pk_bf16_f32 v61, v62, v63
	v_cvt_pk_bf16_f32 v62, v52, v53
	v_cvt_pk_bf16_f32 v63, v54, v55
	v_cvt_pk_bf16_f32 v44, v44, v45
	v_cvt_pk_bf16_f32 v45, v46, v47
	v_cvt_pk_bf16_f32 v46, v36, v37
	v_cvt_pk_bf16_f32 v47, v38, v39
	s_nop 1
	v_permlane16_swap_b32_e32 v60, v62
	v_permlane16_swap_b32_e32 v61, v63
	v_permlane16_swap_b32_e32 v44, v46
	v_permlane16_swap_b32_e32 v45, v47
	global_store_dwordx4 v190, v[60:63], s[72:73] offset:256
	global_store_dwordx4 v190, v[44:47], s[72:73] offset:320
	s_waitcnt vmcnt(18)
	v_lshlrev_b32_e32 v168, 16, v226
	v_and_b32_e32 v169, 0xffff0000, v226
	v_lshlrev_b32_e32 v176, 16, v228
	v_and_b32_e32 v177, 0xffff0000, v228
	v_pk_fma_f32 v[56:57], v[56:57], v[168:169], v[176:177]
	v_lshlrev_b32_e32 v170, 16, v227
	v_and_b32_e32 v171, 0xffff0000, v227
	v_lshlrev_b32_e32 v178, 16, v229
	v_and_b32_e32 v179, 0xffff0000, v229
	v_pk_fma_f32 v[58:59], v[58:59], v[170:171], v[178:179]
	global_load_dwordx2 v[226:227], v137, s[28:29] offset:256
	global_load_dwordx2 v[228:229], v141, s[4:5] offset:256
	s_waitcnt vmcnt(18)
	v_lshlrev_b32_e32 v168, 16, v230
	v_and_b32_e32 v169, 0xffff0000, v230
	v_lshlrev_b32_e32 v176, 16, v232
	v_and_b32_e32 v177, 0xffff0000, v232
	v_pk_fma_f32 v[48:49], v[48:49], v[168:169], v[176:177]
	v_lshlrev_b32_e32 v170, 16, v231
	v_and_b32_e32 v171, 0xffff0000, v231
	v_lshlrev_b32_e32 v178, 16, v233
	v_and_b32_e32 v179, 0xffff0000, v233
	v_pk_fma_f32 v[50:51], v[50:51], v[170:171], v[178:179]
	global_load_dwordx2 v[230:231], v137, s[28:29] offset:288
	global_load_dwordx2 v[232:233], v141, s[4:5] offset:288
	s_waitcnt vmcnt(18)
;     ...
;             for (int n = 0; n < 2; ++n) {
;               const int nc = brow + ai * 128 + wr * 64 + m * 16 + fq * 4;
;               const int tok = bcol + bj * 128 + wc * 32 + n * 16 + fr;
;               const int ncw = brow + ai * 128 + wr * 64 + ((m & ~1) + (fq & 1)) * 16 + (fq & ~1) * 4;
;     ...
;               f32x4 v = acc[ai][bj][m][n];
;               if (MODE == 0) {
;                 if (tn == 52) {
;                   if (ai == 0) *(float4*)((float*)(ws + OFF_DTR) + (size_t)tok * 128 + (nc - 13312)) = make_float4(v[0], v[1], v[2], v[3]);
;                 } else {
;                   u16* dst; int ld, c0;
;                   if (tn < 16) { dst = (u16*)(ws + OFF_Z); ld = 4096; c0 = 0; }
;                   else if (tn < 40) { dst = (u16*)(ws + OFF_RA); ld = 6144; c0 = 4096; }
;                   else if (tn < 48) { dst = (u16*)(ws + OFF_Q); ld = 2048; c0 = 10240; }
;                   else if (tn < 50) { dst = (u16*)(ws + OFF_K); ld = 512; c0 = 12288; }
;                   else { dst = (u16*)(ws + OFF_V); ld = 512; c0 = 12800; }
;                   uint2 o; o.x = pk2(v[0], v[1]); o.y = pk2(v[2], v[3]);
;                   WIDE_STORE(dst, ld, c0, o);
;                 }
;               } else if (MODE == 1) {
;                 uint2 o; o.x = pk2(sigmoidf_(v[0]), sigmoidf_(v[1])); o.y = pk2(sigmoidf_(v[2]), sigmoidf_(v[3]));
;                 WIDE_STORE((u16*)outp, 4096, 0, o);
;               } else if (MODE == 2) {
;                 const u16* gate = (const u16*)outp;
;                 uint2 ga = *(const uint2*)(gate + (size_t)tok * 4096 + nc);
;                 uint2 p1; p1.x = pk2(v[0] * bflo(ga.x), v[1] * bfhi(ga.x)); p1.y = pk2(v[2] * bflo(ga.y), v[3] * bfhi(ga.y));
;                 *(uint2*)((u16*)(ws + OFF_YB) + (size_t)tok * DM + nc) = p1;
;               } else if (MODE == 6) {
;                 const u16* gate = (const u16*)outp;
;                 uint2 gb = *(const uint2*)(gate + (size_t)tok * 4096 + 2048 + nc);
;                 const uint2 p1 = *(const uint2*)((const u16*)(ws + OFF_YB) + (size_t)tok * DM + nc);
;                 uint2 o;
;                 o.x = pk2(bflo(p1.x) + v[0] * bflo(gb.x), bfhi(p1.x) + v[1] * bfhi(gb.x));
;                 o.y = pk2(bflo(p1.y) + v[2] * bflo(gb.y), bfhi(p1.y) + v[3] * bfhi(gb.y));
;                 WIDE_STORE((u16*)(ws + OFF_RB + 128 * MiB), DM, 0, o);
	v_lshlrev_b32_e32 v168, 16, v234
	v_and_b32_e32 v169, 0xffff0000, v234
	v_lshlrev_b32_e32 v176, 16, v236
	v_and_b32_e32 v177, 0xffff0000, v236
	v_pk_fma_f32 v[40:41], v[40:41], v[168:169], v[176:177]
	v_lshlrev_b32_e32 v170, 16, v235
	v_and_b32_e32 v171, 0xffff0000, v235
	v_lshlrev_b32_e32 v178, 16, v237
	v_and_b32_e32 v179, 0xffff0000, v237
	v_pk_fma_f32 v[42:43], v[42:43], v[170:171], v[178:179]
	global_load_dwordx2 v[234:235], v137, s[28:29] offset:320
	global_load_dwordx2 v[236:237], v141, s[4:5] offset:320
	s_waitcnt vmcnt(18)
	v_lshlrev_b32_e32 v168, 16, v238
	v_and_b32_e32 v169, 0xffff0000, v238
	v_lshlrev_b32_e32 v176, 16, v240
	v_and_b32_e32 v177, 0xffff0000, v240
	v_pk_fma_f32 v[32:33], v[32:33], v[168:169], v[176:177]
	v_lshlrev_b32_e32 v170, 16, v239
	v_and_b32_e32 v171, 0xffff0000, v239
	v_lshlrev_b32_e32 v178, 16, v241
	v_and_b32_e32 v179, 0xffff0000, v241
	v_pk_fma_f32 v[34:35], v[34:35], v[170:171], v[178:179]
	global_load_dwordx2 v[238:239], v137, s[28:29] offset:352
	global_load_dwordx2 v[240:241], v141, s[4:5] offset:352
	s_nop 0
	v_cvt_pk_bf16_f32 v56, v56, v57
	v_cvt_pk_bf16_f32 v57, v58, v59
	v_cvt_pk_bf16_f32 v58, v48, v49
	v_cvt_pk_bf16_f32 v59, v50, v51
	v_cvt_pk_bf16_f32 v40, v40, v41
	v_cvt_pk_bf16_f32 v41, v42, v43
	v_cvt_pk_bf16_f32 v42, v32, v33
	v_cvt_pk_bf16_f32 v43, v34, v35
	s_nop 1
	v_permlane16_swap_b32_e32 v56, v58
	v_permlane16_swap_b32_e32 v57, v59
	v_permlane16_swap_b32_e32 v40, v42
	v_permlane16_swap_b32_e32 v41, v43
	global_store_dwordx4 v191, v[56:59], s[72:73] offset:256
	global_store_dwordx4 v191, v[40:43], s[72:73] offset:320
	s_waitcnt vmcnt(18)
	v_lshlrev_b32_e32 v168, 16, v210
	v_and_b32_e32 v169, 0xffff0000, v210
	v_lshlrev_b32_e32 v176, 16, v212
	v_and_b32_e32 v177, 0xffff0000, v212
	v_pk_fma_f32 v[28:29], v[28:29], v[168:169], v[176:177]
	v_lshlrev_b32_e32 v170, 16, v211
	v_and_b32_e32 v171, 0xffff0000, v211
	v_lshlrev_b32_e32 v178, 16, v213
	v_and_b32_e32 v179, 0xffff0000, v213
	v_pk_fma_f32 v[30:31], v[30:31], v[170:171], v[178:179]
	s_waitcnt vmcnt(16)
	v_lshlrev_b32_e32 v168, 16, v214
	v_and_b32_e32 v169, 0xffff0000, v214
	v_lshlrev_b32_e32 v176, 16, v216
	v_and_b32_e32 v177, 0xffff0000, v216
	v_pk_fma_f32 v[20:21], v[20:21], v[168:169], v[176:177]
	v_lshlrev_b32_e32 v170, 16, v215
	v_and_b32_e32 v171, 0xffff0000, v215
	v_lshlrev_b32_e32 v178, 16, v217
	v_and_b32_e32 v179, 0xffff0000, v217
	v_pk_fma_f32 v[22:23], v[22:23], v[170:171], v[178:179]
	s_waitcnt vmcnt(14)
	v_lshlrev_b32_e32 v168, 16, v218
	v_and_b32_e32 v169, 0xffff0000, v218
	v_lshlrev_b32_e32 v176, 16, v220
	v_and_b32_e32 v177, 0xffff0000, v220
	v_pk_fma_f32 v[12:13], v[12:13], v[168:169], v[176:177]
	v_lshlrev_b32_e32 v170, 16, v219
	v_and_b32_e32 v171, 0xffff0000, v219
	v_lshlrev_b32_e32 v178, 16, v221
	v_and_b32_e32 v179, 0xffff0000, v221
	v_pk_fma_f32 v[14:15], v[14:15], v[170:171], v[178:179]
	s_waitcnt vmcnt(12)
	v_lshlrev_b32_e32 v168, 16, v222
	v_and_b32_e32 v169, 0xffff0000, v222
	v_lshlrev_b32_e32 v176, 16, v224
	v_and_b32_e32 v177, 0xffff0000, v224
	v_pk_fma_f32 v[4:5], v[4:5], v[168:169], v[176:177]
	v_lshlrev_b32_e32 v170, 16, v223
	v_and_b32_e32 v171, 0xffff0000, v223
	v_lshlrev_b32_e32 v178, 16, v225
	v_and_b32_e32 v179, 0xffff0000, v225
	v_pk_fma_f32 v[6:7], v[6:7], v[170:171], v[178:179]
	s_nop 0
	v_cvt_pk_bf16_f32 v28, v28, v29
	v_cvt_pk_bf16_f32 v29, v30, v31
	v_cvt_pk_bf16_f32 v30, v20, v21
	v_cvt_pk_bf16_f32 v31, v22, v23
	v_cvt_pk_bf16_f32 v12, v12, v13
	v_cvt_pk_bf16_f32 v13, v14, v15
	v_cvt_pk_bf16_f32 v14, v4, v5
	v_cvt_pk_bf16_f32 v15, v6, v7
	s_nop 1
	v_permlane16_swap_b32_e32 v28, v30
	v_permlane16_swap_b32_e32 v29, v31
	v_permlane16_swap_b32_e32 v12, v14
	v_permlane16_swap_b32_e32 v13, v15
	global_store_dwordx4 v192, v[28:31], s[72:73] offset:256
	global_store_dwordx4 v192, v[12:15], s[72:73] offset:320
	s_waitcnt vmcnt(10)
	v_lshlrev_b32_e32 v168, 16, v226
	v_and_b32_e32 v169, 0xffff0000, v226
	v_lshlrev_b32_e32 v176, 16, v228
	v_and_b32_e32 v177, 0xffff0000, v228
	v_pk_fma_f32 v[24:25], v[24:25], v[168:169], v[176:177]
	v_lshlrev_b32_e32 v170, 16, v227
	v_and_b32_e32 v171, 0xffff0000, v227
	v_lshlrev_b32_e32 v178, 16, v229
	v_and_b32_e32 v179, 0xffff0000, v229
	v_pk_fma_f32 v[26:27], v[26:27], v[170:171], v[178:179]
	s_waitcnt vmcnt(8)
	v_lshlrev_b32_e32 v168, 16, v230
	v_and_b32_e32 v169, 0xffff0000, v230
	v_lshlrev_b32_e32 v176, 16, v232
	v_and_b32_e32 v177, 0xffff0000, v232
	v_pk_fma_f32 v[16:17], v[16:17], v[168:169], v[176:177]
	v_lshlrev_b32_e32 v170, 16, v231
	v_and_b32_e32 v171, 0xffff0000, v231
	v_lshlrev_b32_e32 v178, 16, v233
	v_and_b32_e32 v179, 0xffff0000, v233
	v_pk_fma_f32 v[18:19], v[18:19], v[170:171], v[178:179]
	s_waitcnt vmcnt(6)
	v_lshlrev_b32_e32 v168, 16, v234
	v_and_b32_e32 v169, 0xffff0000, v234
	v_lshlrev_b32_e32 v176, 16, v236
	v_and_b32_e32 v177, 0xffff0000, v236
	v_pk_fma_f32 v[8:9], v[8:9], v[168:169], v[176:177]
	v_lshlrev_b32_e32 v170, 16, v235
	v_and_b32_e32 v171, 0xffff0000, v235
	v_lshlrev_b32_e32 v178, 16, v237
	v_and_b32_e32 v179, 0xffff0000, v237
	v_pk_fma_f32 v[10:11], v[10:11], v[170:171], v[178:179]
	s_waitcnt vmcnt(4)
	v_lshlrev_b32_e32 v168, 16, v238
	v_and_b32_e32 v169, 0xffff0000, v238
	v_lshlrev_b32_e32 v176, 16, v240
	v_and_b32_e32 v177, 0xffff0000, v240
	v_pk_fma_f32 v[0:1], v[0:1], v[168:169], v[176:177]
	v_lshlrev_b32_e32 v170, 16, v239
	v_and_b32_e32 v171, 0xffff0000, v239
	v_lshlrev_b32_e32 v178, 16, v241
	v_and_b32_e32 v179, 0xffff0000, v241
	v_pk_fma_f32 v[2:3], v[2:3], v[170:171], v[178:179]
	s_nop 0
	v_cvt_pk_bf16_f32 v24, v24, v25
	v_cvt_pk_bf16_f32 v25, v26, v27
	v_cvt_pk_bf16_f32 v26, v16, v17
	v_cvt_pk_bf16_f32 v27, v18, v19
	v_cvt_pk_bf16_f32 v8, v8, v9
	v_cvt_pk_bf16_f32 v9, v10, v11
	v_cvt_pk_bf16_f32 v10, v0, v1
	v_cvt_pk_bf16_f32 v11, v2, v3
	s_nop 1
	v_permlane16_swap_b32_e32 v24, v26
	v_permlane16_swap_b32_e32 v25, v27
	v_permlane16_swap_b32_e32 v8, v10
	v_permlane16_swap_b32_e32 v9, v11
	global_store_dwordx4 v193, v[24:27], s[72:73] offset:256
	global_store_dwordx4 v193, v[8:11], s[72:73] offset:320
	s_and_b64 s[0:1], s[56:57], s[8:9]
	s_andn2_b64 vcc, exec, s[0:1]
	s_waitcnt vmcnt(0)
	s_cbranch_vccnz .LBB0_819
	s_barrier
	s_branch .LBB0_819

;     ...
;             for (int n = 0; n < 2; ++n) {
;               const int nc = brow + ai * 128 + wr * 64 + m * 16 + fq * 4;
;               const int tok = bcol + bj * 128 + wc * 32 + n * 16 + fr;
;               const int ncw = brow + ai * 128 + wr * 64 + ((m & ~1) + (fq & 1)) * 16 + (fq & ~1) * 4;
;     ...
;               f32x4 v = acc[ai][bj][m][n];
;               if (MODE == 0) {
;                 if (tn == 52) {
;                   if (ai == 0) *(float4*)((float*)(ws + OFF_DTR) + (size_t)tok * 128 + (nc - 13312)) = make_float4(v[0], v[1], v[2], v[3]);
;                 } else {
;                   u16* dst; int ld, c0;
;                   if (tn < 16) { dst = (u16*)(ws + OFF_Z); ld = 4096; c0 = 0; }
;                   else if (tn < 40) { dst = (u16*)(ws + OFF_RA); ld = 6144; c0 = 4096; }
;                   else if (tn < 48) { dst = (u16*)(ws + OFF_Q); ld = 2048; c0 = 10240; }
;                   else if (tn < 50) { dst = (u16*)(ws + OFF_K); ld = 512; c0 = 12288; }
;                   else { dst = (u16*)(ws + OFF_V); ld = 512; c0 = 12800; }
;                   uint2 o; o.x = pk2(v[0], v[1]); o.y = pk2(v[2], v[3]);
;                   WIDE_STORE(dst, ld, c0, o);
;                 }
;               } else if (MODE == 1) {
;                 uint2 o; o.x = pk2(sigmoidf_(v[0]), sigmoidf_(v[1])); o.y = pk2(sigmoidf_(v[2]), sigmoidf_(v[3]));
;                 WIDE_STORE((u16*)outp, 4096, 0, o);
;               } else if (MODE == 2) {
;                 const u16* gate = (const u16*)outp;
;                 uint2 ga = *(const uint2*)(gate + (size_t)tok * 4096 + nc);
;                 uint2 p1; p1.x = pk2(v[0] * bflo(ga.x), v[1] * bfhi(ga.x)); p1.y = pk2(v[2] * bflo(ga.y), v[3] * bfhi(ga.y));
;                 *(uint2*)((u16*)(ws + OFF_YB) + (size_t)tok * DM + nc) = p1;
;               } else if (MODE == 6) {
;                 const u16* gate = (const u16*)outp;
;                 uint2 gb = *(const uint2*)(gate + (size_t)tok * 4096 + 2048 + nc);
;                 const uint2 p1 = *(const uint2*)((const u16*)(ws + OFF_YB) + (size_t)tok * DM + nc);
;                 uint2 o;
;                 o.x = pk2(bflo(p1.x) + v[0] * bflo(gb.x), bfhi(p1.x) + v[1] * bfhi(gb.x));
;                 o.y = pk2(bflo(p1.y) + v[2] * bflo(gb.y), bfhi(p1.y) + v[3] * bfhi(gb.y));
;                 WIDE_STORE((u16*)(ws + OFF_RB + 128 * MiB), DM, 0, o);
;               } else if (MODE == 3) {
.LBB0_1086:
	v_readlane_b32 s26, v245, 25
	v_readlane_b32 s27, v245, 26
	v_readlane_b32 s34, v243, 2
	v_readlane_b32 s31, v244, 61
	v_readlane_b32 s35, v243, 3
	s_add_i32 s0, s23, s49
	v_and_b32_e32 v172, 15, v150
	v_or_b32_e32 v172, s54, v172
	v_or_b32_e32 v172, s24, v172
	v_lshrrev_b32_e32 v173, 2, v150
	v_and_b32_e32 v174, -4, v173
	v_add_u32_e32 v174, s0, v174
	v_and_b32_e32 v173, -8, v173
	v_and_b32_e32 v175, 16, v150
	v_add3_u32 v173, v173, v175, s0
	v_lshlrev_b32_e32 v175, 12, v172
	v_lshl_add_u32 v134, v174, 1, v175
	v_add_u32_e32 v135, 0x10000, v134
	v_add_u32_e32 v136, 0x80000, v134
	v_add_u32_e32 v137, 0x90000, v134
	v_lshlrev_b32_e32 v175, 12, v172
	v_lshl_add_u32 v138, v173, 1, v175
	v_add_u32_e32 v139, 0x10000, v138
	v_add_u32_e32 v140, 0x80000, v138
	v_add_u32_e32 v141, 0x90000, v138
	global_load_dwordx2 v[210:211], v134, s[26:27] offset:0
	global_load_dwordx2 v[212:213], v134, s[26:27] offset:32
	global_load_dwordx2 v[214:215], v134, s[26:27] offset:64
	global_load_dwordx2 v[216:217], v134, s[26:27] offset:96
	global_load_dwordx2 v[218:219], v135, s[26:27] offset:0
	global_load_dwordx2 v[220:221], v135, s[26:27] offset:32
	global_load_dwordx2 v[222:223], v135, s[26:27] offset:64
	global_load_dwordx2 v[224:225], v135, s[26:27] offset:96
	global_load_dwordx2 v[226:227], v136, s[26:27] offset:0
	global_load_dwordx2 v[228:229], v136, s[26:27] offset:32
	global_load_dwordx2 v[230:231], v136, s[26:27] offset:64
	global_load_dwordx2 v[232:233], v136, s[26:27] offset:96
	global_load_dwordx2 v[234:235], v137, s[26:27] offset:0
	global_load_dwordx2 v[236:237], v137, s[26:27] offset:32
	global_load_dwordx2 v[238:239], v137, s[26:27] offset:64
	global_load_dwordx2 v[240:241], v137, s[26:27] offset:96
	s_waitcnt vmcnt(15)
	v_lshlrev_b32_e32 v168, 16, v210
	v_and_b32_e32 v169, 0xffff0000, v210
	v_lshlrev_b32_e32 v170, 16, v211
	v_and_b32_e32 v171, 0xffff0000, v211
	v_pk_add_f32 v[124:125], v[124:125], v[168:169]
	v_pk_add_f32 v[126:127], v[126:127], v[170:171]
	global_load_dwordx2 v[210:211], v134, s[26:27] offset:256
	s_waitcnt vmcnt(15)
	v_lshlrev_b32_e32 v168, 16, v212
	v_and_b32_e32 v169, 0xffff0000, v212
	v_lshlrev_b32_e32 v170, 16, v213
	v_and_b32_e32 v171, 0xffff0000, v213
	v_pk_add_f32 v[116:117], v[116:117], v[168:169]
	v_pk_add_f32 v[118:119], v[118:119], v[170:171]
	global_load_dwordx2 v[212:213], v134, s[26:27] offset:288
	s_waitcnt vmcnt(15)
	v_lshlrev_b32_e32 v168, 16, v214
	v_and_b32_e32 v169, 0xffff0000, v214
	v_lshlrev_b32_e32 v170, 16, v215
	v_and_b32_e32 v171, 0xffff0000, v215
	v_pk_add_f32 v[108:109], v[108:109], v[168:169]
	v_pk_add_f32 v[110:111], v[110:111], v[170:171]
	global_load_dwordx2 v[214:215], v134, s[26:27] offset:320
	s_waitcnt vmcnt(15)
	v_lshlrev_b32_e32 v168, 16, v216
	v_and_b32_e32 v169, 0xffff0000, v216
	v_lshlrev_b32_e32 v170, 16, v217
	v_and_b32_e32 v171, 0xffff0000, v217
	v_pk_add_f32 v[100:101], v[100:101], v[168:169]
	v_pk_add_f32 v[102:103], v[102:103], v[170:171]
	global_load_dwordx2 v[216:217], v134, s[26:27] offset:352
	s_nop 0
	v_cvt_pk_bf16_f32 v124, v124, v125
	v_cvt_pk_bf16_f32 v125, v126, v127
	v_cvt_pk_bf16_f32 v126, v116, v117
	v_cvt_pk_bf16_f32 v127, v118, v119
	v_cvt_pk_bf16_f32 v108, v108, v109
	v_cvt_pk_bf16_f32 v109, v110, v111
	v_cvt_pk_bf16_f32 v110, v100, v101
	v_cvt_pk_bf16_f32 v111, v102, v103
	s_nop 1
	v_permlane16_swap_b32_e32 v124, v126
	v_permlane16_swap_b32_e32 v125, v127
	v_permlane16_swap_b32_e32 v108, v110
	v_permlane16_swap_b32_e32 v109, v111
	global_store_dwordx4 v138, v[124:127], s[26:27] offset:0
	global_store_dwordx4 v138, v[108:111], s[26:27] offset:64
	s_waitcnt vmcnt(17)
	v_lshlrev_b32_e32 v168, 16, v218
	v_and_b32_e32 v169, 0xffff0000, v218
	v_lshlrev_b32_e32 v170, 16, v219
	v_and_b32_e32 v171, 0xffff0000, v219
	v_pk_add_f32 v[120:121], v[120:121], v[168:169]
	v_pk_add_f32 v[122:123], v[122:123], v[170:171]
	global_load_dwordx2 v[218:219], v135, s[26:27] offset:256
	s_waitcnt vmcnt(17)
	v_lshlrev_b32_e32 v168, 16, v220
	v_and_b32_e32 v169, 0xffff0000, v220
	v_lshlrev_b32_e32 v170, 16, v221
	v_and_b32_e32 v171, 0xffff0000, v221
	v_pk_add_f32 v[112:113], v[112:113], v[168:169]
	v_pk_add_f32 v[114:115], v[114:115], v[170:171]
	global_load_dwordx2 v[220:221], v135, s[26:27] offset:288
	s_waitcnt vmcnt(17)
	v_lshlrev_b32_e32 v168, 16, v222
	v_and_b32_e32 v169, 0xffff0000, v222
	v_lshlrev_b32_e32 v170, 16, v223
	v_and_b32_e32 v171, 0xffff0000, v223
	v_pk_add_f32 v[104:105], v[104:105], v[168:169]
	v_pk_add_f32 v[106:107], v[106:107], v[170:171]
	global_load_dwordx2 v[222:223], v135, s[26:27] offset:320
	s_waitcnt vmcnt(17)
	v_lshlrev_b32_e32 v168, 16, v224
	v_and_b32_e32 v169, 0xffff0000, v224
	v_lshlrev_b32_e32 v170, 16, v225
	v_and_b32_e32 v171, 0xffff0000, v225
	v_pk_add_f32 v[96:97], v[96:97], v[168:169]
	v_pk_add_f32 v[98:99], v[98:99], v[170:171]
	global_load_dwordx2 v[224:225], v135, s[26:27] offset:352
	s_nop 0
	v_cvt_pk_bf16_f32 v120, v120, v121
	v_cvt_pk_bf16_f32 v121, v122, v123
	v_cvt_pk_bf16_f32 v122, v112, v113
	v_cvt_pk_bf16_f32 v123, v114, v115
	v_cvt_pk_bf16_f32 v104, v104, v105
	v_cvt_pk_bf16_f32 v105, v106, v107
	v_cvt_pk_bf16_f32 v106, v96, v97
	v_cvt_pk_bf16_f32 v107, v98, v99
	s_nop 1
	v_permlane16_swap_b32_e32 v120, v122
	v_permlane16_swap_b32_e32 v121, v123
	v_permlane16_swap_b32_e32 v104, v106
	v_permlane16_swap_b32_e32 v105, v107
	global_store_dwordx4 v139, v[120:123], s[26:27] offset:0
	global_store_dwordx4 v139, v[104:107], s[26:27] offset:64
	s_waitcnt vmcnt(19)
	v_lshlrev_b32_e32 v168, 16, v226
	v_and_b32_e32 v169, 0xffff0000, v226
	v_lshlrev_b32_e32 v170, 16, v227
	v_and_b32_e32 v171, 0xffff0000, v227
	v_pk_add_f32 v[92:93], v[92:93], v[168:169]
	v_pk_add_f32 v[94:95], v[94:95], v[170:171]
	global_load_dwordx2 v[226:227], v136, s[26:27] offset:256
	s_waitcnt vmcnt(19)
;     ...
;             for (int n = 0; n < 2; ++n) {
;               const int nc = brow + ai * 128 + wr * 64 + m * 16 + fq * 4;
;               const int tok = bcol + bj * 128 + wc * 32 + n * 16 + fr;
;               const int ncw = brow + ai * 128 + wr * 64 + ((m & ~1) + (fq & 1)) * 16 + (fq & ~1) * 4;
;     ...
;               f32x4 v = acc[ai][bj][m][n];
;               if (MODE == 0) {
;                 if (tn == 52) {
;                   if (ai == 0) *(float4*)((float*)(ws + OFF_DTR) + (size_t)tok * 128 + (nc - 13312)) = make_float4(v[0], v[1], v[2], v[3]);
;                 } else {
;                   u16* dst; int ld, c0;
;                   if (tn < 16) { dst = (u16*)(ws + OFF_Z); ld = 4096; c0 = 0; }
;                   else if (tn < 40) { dst = (u16*)(ws + OFF_RA); ld = 6144; c0 = 4096; }
;                   else if (tn < 48) { dst = (u16*)(ws + OFF_Q); ld = 2048; c0 = 10240; }
;                   else if (tn < 50) { dst = (u16*)(ws + OFF_K); ld = 512; c0 = 12288; }
;                   else { dst = (u16*)(ws + OFF_V); ld = 512; c0 = 12800; }
;                   uint2 o; o.x = pk2(v[0], v[1]); o.y = pk2(v[2], v[3]);
;                   WIDE_STORE(dst, ld, c0, o);
;                 }
;               } else if (MODE == 1) {
;                 uint2 o; o.x = pk2(sigmoidf_(v[0]), sigmoidf_(v[1])); o.y = pk2(sigmoidf_(v[2]), sigmoidf_(v[3]));
;                 WIDE_STORE((u16*)outp, 4096, 0, o);
;               } else if (MODE == 2) {
;                 const u16* gate = (const u16*)outp;
;                 uint2 ga = *(const uint2*)(gate + (size_t)tok * 4096 + nc);
;                 uint2 p1; p1.x = pk2(v[0] * bflo(ga.x), v[1] * bfhi(ga.x)); p1.y = pk2(v[2] * bflo(ga.y), v[3] * bfhi(ga.y));
;                 *(uint2*)((u16*)(ws + OFF_YB) + (size_t)tok * DM + nc) = p1;
;               } else if (MODE == 6) {
;                 const u16* gate = (const u16*)outp;
;                 uint2 gb = *(const uint2*)(gate + (size_t)tok * 4096 + 2048 + nc);
;                 const uint2 p1 = *(const uint2*)((const u16*)(ws + OFF_YB) + (size_t)tok * DM + nc);
;                 uint2 o;
;                 o.x = pk2(bflo(p1.x) + v[0] * bflo(gb.x), bfhi(p1.x) + v[1] * bfhi(gb.x));
;                 o.y = pk2(bflo(p1.y) + v[2] * bflo(gb.y), bfhi(p1.y) + v[3] * bfhi(gb.y));
;                 WIDE_STORE((u16*)(ws + OFF_RB + 128 * MiB), DM, 0, o);
;               } else if (MODE == 3) {
	v_lshlrev_b32_e32 v168, 16, v228
	v_and_b32_e32 v169, 0xffff0000, v228
	v_lshlrev_b32_e32 v170, 16, v229
	v_and_b32_e32 v171, 0xffff0000, v229
	v_pk_add_f32 v[84:85], v[84:85], v[168:169]
	v_pk_add_f32 v[86:87], v[86:87], v[170:171]
	global_load_dwordx2 v[228:229], v136, s[26:27] offset:288
	s_waitcnt vmcnt(19)
	v_lshlrev_b32_e32 v168, 16, v230
	v_and_b32_e32 v169, 0xffff0000, v230
	v_lshlrev_b32_e32 v170, 16, v231
	v_and_b32_e32 v171, 0xffff0000, v231
	v_pk_add_f32 v[76:77], v[76:77], v[168:169]
	v_pk_add_f32 v[78:79], v[78:79], v[170:171]
	global_load_dwordx2 v[230:231], v136, s[26:27] offset:320
	s_waitcnt vmcnt(19)
	v_lshlrev_b32_e32 v168, 16, v232
	v_and_b32_e32 v169, 0xffff0000, v232
	v_lshlrev_b32_e32 v170, 16, v233
	v_and_b32_e32 v171, 0xffff0000, v233
	v_pk_add_f32 v[68:69], v[68:69], v[168:169]
	v_pk_add_f32 v[70:71], v[70:71], v[170:171]
	global_load_dwordx2 v[232:233], v136, s[26:27] offset:352
	s_nop 0
	v_cvt_pk_bf16_f32 v92, v92, v93
	v_cvt_pk_bf16_f32 v93, v94, v95
	v_cvt_pk_bf16_f32 v94, v84, v85
	v_cvt_pk_bf16_f32 v95, v86, v87
	v_cvt_pk_bf16_f32 v76, v76, v77
	v_cvt_pk_bf16_f32 v77, v78, v79
	v_cvt_pk_bf16_f32 v78, v68, v69
	v_cvt_pk_bf16_f32 v79, v70, v71
	s_nop 1
	v_permlane16_swap_b32_e32 v92, v94
	v_permlane16_swap_b32_e32 v93, v95
	v_permlane16_swap_b32_e32 v76, v78
	v_permlane16_swap_b32_e32 v77, v79
	global_store_dwordx4 v140, v[92:95], s[26:27] offset:0
	global_store_dwordx4 v140, v[76:79], s[26:27] offset:64
	s_waitcnt vmcnt(21)
	v_lshlrev_b32_e32 v168, 16, v234
	v_and_b32_e32 v169, 0xffff0000, v234
	v_lshlrev_b32_e32 v170, 16, v235
	v_and_b32_e32 v171, 0xffff0000, v235
	v_pk_add_f32 v[88:89], v[88:89], v[168:169]
	v_pk_add_f32 v[90:91], v[90:91], v[170:171]
	global_load_dwordx2 v[234:235], v137, s[26:27] offset:256
	s_waitcnt vmcnt(21)
	v_lshlrev_b32_e32 v168, 16, v236
	v_and_b32_e32 v169, 0xffff0000, v236
	v_lshlrev_b32_e32 v170, 16, v237
	v_and_b32_e32 v171, 0xffff0000, v237
	v_pk_add_f32 v[80:81], v[80:81], v[168:169]
	v_pk_add_f32 v[82:83], v[82:83], v[170:171]
	global_load_dwordx2 v[236:237], v137, s[26:27] offset:288
	s_waitcnt vmcnt(21)
	v_lshlrev_b32_e32 v168, 16, v238
	v_and_b32_e32 v169, 0xffff0000, v238
	v_lshlrev_b32_e32 v170, 16, v239
	v_and_b32_e32 v171, 0xffff0000, v239
	v_pk_add_f32 v[72:73], v[72:73], v[168:169]
	v_pk_add_f32 v[74:75], v[74:75], v[170:171]
	global_load_dwordx2 v[238:239], v137, s[26:27] offset:320
	s_waitcnt vmcnt(21)
	v_lshlrev_b32_e32 v168, 16, v240
	v_and_b32_e32 v169, 0xffff0000, v240
	v_lshlrev_b32_e32 v170, 16, v241
	v_and_b32_e32 v171, 0xffff0000, v241
	v_pk_add_f32 v[64:65], v[64:65], v[168:169]
	v_pk_add_f32 v[66:67], v[66:67], v[170:171]
	global_load_dwordx2 v[240:241], v137, s[26:27] offset:352
	s_nop 0
	v_cvt_pk_bf16_f32 v88, v88, v89
	v_cvt_pk_bf16_f32 v89, v90, v91
	v_cvt_pk_bf16_f32 v90, v80, v81
	v_cvt_pk_bf16_f32 v91, v82, v83
	v_cvt_pk_bf16_f32 v72, v72, v73
	v_cvt_pk_bf16_f32 v73, v74, v75
	v_cvt_pk_bf16_f32 v74, v64, v65
	v_cvt_pk_bf16_f32 v75, v66, v67
	s_nop 1
	v_permlane16_swap_b32_e32 v88, v90
	v_permlane16_swap_b32_e32 v89, v91
	v_permlane16_swap_b32_e32 v72, v74
	v_permlane16_swap_b32_e32 v73, v75
	global_store_dwordx4 v141, v[88:91], s[26:27] offset:0
	global_store_dwordx4 v141, v[72:75], s[26:27] offset:64
	s_waitcnt vmcnt(23)
	v_lshlrev_b32_e32 v168, 16, v210
	v_and_b32_e32 v169, 0xffff0000, v210
	v_lshlrev_b32_e32 v170, 16, v211
	v_and_b32_e32 v171, 0xffff0000, v211
	v_pk_add_f32 v[60:61], v[60:61], v[168:169]
	v_pk_add_f32 v[62:63], v[62:63], v[170:171]
	s_waitcnt vmcnt(22)
	v_lshlrev_b32_e32 v168, 16, v212
	v_and_b32_e32 v169, 0xffff0000, v212
	v_lshlrev_b32_e32 v170, 16, v213
	v_and_b32_e32 v171, 0xffff0000, v213
	v_pk_add_f32 v[52:53], v[52:53], v[168:169]
	v_pk_add_f32 v[54:55], v[54:55], v[170:171]
	s_waitcnt vmcnt(21)
	v_lshlrev_b32_e32 v168, 16, v214
	v_and_b32_e32 v169, 0xffff0000, v214
	v_lshlrev_b32_e32 v170, 16, v215
	v_and_b32_e32 v171, 0xffff0000, v215
	v_pk_add_f32 v[44:45], v[44:45], v[168:169]
	v_pk_add_f32 v[46:47], v[46:47], v[170:171]
	s_waitcnt vmcnt(20)
	v_lshlrev_b32_e32 v168, 16, v216
	v_and_b32_e32 v169, 0xffff0000, v216
	v_lshlrev_b32_e32 v170, 16, v217
	v_and_b32_e32 v171, 0xffff0000, v217
	v_pk_add_f32 v[36:37], v[36:37], v[168:169]
	v_pk_add_f32 v[38:39], v[38:39], v[170:171]
	s_nop 0
	v_cvt_pk_bf16_f32 v60, v60, v61
	v_cvt_pk_bf16_f32 v61, v62, v63
	v_cvt_pk_bf16_f32 v62, v52, v53
	v_cvt_pk_bf16_f32 v63, v54, v55
	v_cvt_pk_bf16_f32 v44, v44, v45
	v_cvt_pk_bf16_f32 v45, v46, v47
	v_cvt_pk_bf16_f32 v46, v36, v37
	v_cvt_pk_bf16_f32 v47, v38, v39
	s_nop 1
	v_permlane16_swap_b32_e32 v60, v62
	v_permlane16_swap_b32_e32 v61, v63
	v_permlane16_swap_b32_e32 v44, v46
	v_permlane16_swap_b32_e32 v45, v47
	global_store_dwordx4 v138, v[60:63], s[26:27] offset:256
	global_store_dwordx4 v138, v[44:47], s[26:27] offset:320
	s_waitcnt vmcnt(19)
;     ...
;             for (int n = 0; n < 2; ++n) {
;               const int nc = brow + ai * 128 + wr * 64 + m * 16 + fq * 4;
;               const int tok = bcol + bj * 128 + wc * 32 + n * 16 + fr;
;               const int ncw = brow + ai * 128 + wr * 64 + ((m & ~1) + (fq & 1)) * 16 + (fq & ~1) * 4;
;     ...
;               f32x4 v = acc[ai][bj][m][n];
;               if (MODE == 0) {
;                 if (tn == 52) {
;                   if (ai == 0) *(float4*)((float*)(ws + OFF_DTR) + (size_t)tok * 128 + (nc - 13312)) = make_float4(v[0], v[1], v[2], v[3]);
;                 } else {
;                   u16* dst; int ld, c0;
;                   if (tn < 16) { dst = (u16*)(ws + OFF_Z); ld = 4096; c0 = 0; }
;                   else if (tn < 40) { dst = (u16*)(ws + OFF_RA); ld = 6144; c0 = 4096; }
;                   else if (tn < 48) { dst = (u16*)(ws + OFF_Q); ld = 2048; c0 = 10240; }
;                   else if (tn < 50) { dst = (u16*)(ws + OFF_K); ld = 512; c0 = 12288; }
;                   else { dst = (u16*)(ws + OFF_V); ld = 512; c0 = 12800; }
;                   uint2 o; o.x = pk2(v[0], v[1]); o.y = pk2(v[2], v[3]);
;                   WIDE_STORE(dst, ld, c0, o);
;                 }
;               } else if (MODE == 1) {
;                 uint2 o; o.x = pk2(sigmoidf_(v[0]), sigmoidf_(v[1])); o.y = pk2(sigmoidf_(v[2]), sigmoidf_(v[3]));
;                 WIDE_STORE((u16*)outp, 4096, 0, o);
;               } else if (MODE == 2) {
;                 const u16* gate = (const u16*)outp;
;                 uint2 ga = *(const uint2*)(gate + (size_t)tok * 4096 + nc);
;                 uint2 p1; p1.x = pk2(v[0] * bflo(ga.x), v[1] * bfhi(ga.x)); p1.y = pk2(v[2] * bflo(ga.y), v[3] * bfhi(ga.y));
;                 *(uint2*)((u16*)(ws + OFF_YB) + (size_t)tok * DM + nc) = p1;
;               } else if (MODE == 6) {
;                 const u16* gate = (const u16*)outp;
;                 uint2 gb = *(const uint2*)(gate + (size_t)tok * 4096 + 2048 + nc);
;                 const uint2 p1 = *(const uint2*)((const u16*)(ws + OFF_YB) + (size_t)tok * DM + nc);
;                 uint2 o;
;                 o.x = pk2(bflo(p1.x) + v[0] * bflo(gb.x), bfhi(p1.x) + v[1] * bfhi(gb.x));
;                 o.y = pk2(bflo(p1.y) + v[2] * bflo(gb.y), bfhi(p1.y) + v[3] * bfhi(gb.y));
;                 WIDE_STORE((u16*)(ws + OFF_RB + 128 * MiB), DM, 0, o);
;               } else if (MODE == 3) {
	v_lshlrev_b32_e32 v168, 16, v218
	v_and_b32_e32 v169, 0xffff0000, v218
	v_lshlrev_b32_e32 v170, 16, v219
	v_and_b32_e32 v171, 0xffff0000, v219
	v_pk_add_f32 v[56:57], v[56:57], v[168:169]
	v_pk_add_f32 v[58:59], v[58:59], v[170:171]
	s_waitcnt vmcnt(18)
	v_lshlrev_b32_e32 v168, 16, v220
	v_and_b32_e32 v169, 0xffff0000, v220
	v_lshlrev_b32_e32 v170, 16, v221
	v_and_b32_e32 v171, 0xffff0000, v221
	v_pk_add_f32 v[48:49], v[48:49], v[168:169]
	v_pk_add_f32 v[50:51], v[50:51], v[170:171]
	s_waitcnt vmcnt(17)
	v_lshlrev_b32_e32 v168, 16, v222
	v_and_b32_e32 v169, 0xffff0000, v222
	v_lshlrev_b32_e32 v170, 16, v223
	v_and_b32_e32 v171, 0xffff0000, v223
	v_pk_add_f32 v[40:41], v[40:41], v[168:169]
	v_pk_add_f32 v[42:43], v[42:43], v[170:171]
	s_waitcnt vmcnt(16)
	v_lshlrev_b32_e32 v168, 16, v224
	v_and_b32_e32 v169, 0xffff0000, v224
	v_lshlrev_b32_e32 v170, 16, v225
	v_and_b32_e32 v171, 0xffff0000, v225
	v_pk_add_f32 v[32:33], v[32:33], v[168:169]
	v_pk_add_f32 v[34:35], v[34:35], v[170:171]
	s_nop 0
	v_cvt_pk_bf16_f32 v56, v56, v57
	v_cvt_pk_bf16_f32 v57, v58, v59
	v_cvt_pk_bf16_f32 v58, v48, v49
	v_cvt_pk_bf16_f32 v59, v50, v51
	v_cvt_pk_bf16_f32 v40, v40, v41
	v_cvt_pk_bf16_f32 v41, v42, v43
	v_cvt_pk_bf16_f32 v42, v32, v33
	v_cvt_pk_bf16_f32 v43, v34, v35
	s_nop 1
	v_permlane16_swap_b32_e32 v56, v58
	v_permlane16_swap_b32_e32 v57, v59
	v_permlane16_swap_b32_e32 v40, v42
	v_permlane16_swap_b32_e32 v41, v43
	global_store_dwordx4 v139, v[56:59], s[26:27] offset:256
	global_store_dwordx4 v139, v[40:43], s[26:27] offset:320
	s_waitcnt vmcnt(15)
	v_lshlrev_b32_e32 v168, 16, v226
	v_and_b32_e32 v169, 0xffff0000, v226
	v_lshlrev_b32_e32 v170, 16, v227
	v_and_b32_e32 v171, 0xffff0000, v227
	v_pk_add_f32 v[28:29], v[28:29], v[168:169]
	v_pk_add_f32 v[30:31], v[30:31], v[170:171]
	s_waitcnt vmcnt(14)
	v_lshlrev_b32_e32 v168, 16, v228
	v_and_b32_e32 v169, 0xffff0000, v228
	v_lshlrev_b32_e32 v170, 16, v229
	v_and_b32_e32 v171, 0xffff0000, v229
	v_pk_add_f32 v[20:21], v[20:21], v[168:169]
	v_pk_add_f32 v[22:23], v[22:23], v[170:171]
	s_waitcnt vmcnt(13)
	v_lshlrev_b32_e32 v168, 16, v230
	v_and_b32_e32 v169, 0xffff0000, v230
	v_lshlrev_b32_e32 v170, 16, v231
	v_and_b32_e32 v171, 0xffff0000, v231
	v_pk_add_f32 v[12:13], v[12:13], v[168:169]
	v_pk_add_f32 v[14:15], v[14:15], v[170:171]
	s_waitcnt vmcnt(12)
	v_lshlrev_b32_e32 v168, 16, v232
	v_and_b32_e32 v169, 0xffff0000, v232
	v_lshlrev_b32_e32 v170, 16, v233
	v_and_b32_e32 v171, 0xffff0000, v233
	v_pk_add_f32 v[4:5], v[4:5], v[168:169]
	v_pk_add_f32 v[6:7], v[6:7], v[170:171]
	s_nop 0
	v_cvt_pk_bf16_f32 v28, v28, v29
	v_cvt_pk_bf16_f32 v29, v30, v31
	v_cvt_pk_bf16_f32 v30, v20, v21
	v_cvt_pk_bf16_f32 v31, v22, v23
	v_cvt_pk_bf16_f32 v12, v12, v13
	v_cvt_pk_bf16_f32 v13, v14, v15
	v_cvt_pk_bf16_f32 v14, v4, v5
	v_cvt_pk_bf16_f32 v15, v6, v7
	s_nop 1
	v_permlane16_swap_b32_e32 v28, v30
	v_permlane16_swap_b32_e32 v29, v31
	v_permlane16_swap_b32_e32 v12, v14
	v_permlane16_swap_b32_e32 v13, v15
	global_store_dwordx4 v140, v[28:31], s[26:27] offset:256
	global_store_dwordx4 v140, v[12:15], s[26:27] offset:320
	s_waitcnt vmcnt(11)
	v_lshlrev_b32_e32 v168, 16, v234
	v_and_b32_e32 v169, 0xffff0000, v234
	v_lshlrev_b32_e32 v170, 16, v235
	v_and_b32_e32 v171, 0xffff0000, v235
	v_pk_add_f32 v[24:25], v[24:25], v[168:169]
	v_pk_add_f32 v[26:27], v[26:27], v[170:171]
	s_waitcnt vmcnt(10)
	v_lshlrev_b32_e32 v168, 16, v236
	v_and_b32_e32 v169, 0xffff0000, v236
	v_lshlrev_b32_e32 v170, 16, v237
	v_and_b32_e32 v171, 0xffff0000, v237
	v_pk_add_f32 v[16:17], v[16:17], v[168:169]
	v_pk_add_f32 v[18:19], v[18:19], v[170:171]
	s_waitcnt vmcnt(9)
	v_lshlrev_b32_e32 v168, 16, v238
	v_and_b32_e32 v169, 0xffff0000, v238
	v_lshlrev_b32_e32 v170, 16, v239
	v_and_b32_e32 v171, 0xffff0000, v239
	v_pk_add_f32 v[8:9], v[8:9], v[168:169]
	v_pk_add_f32 v[10:11], v[10:11], v[170:171]
	s_waitcnt vmcnt(8)
	v_lshlrev_b32_e32 v168, 16, v240
	v_and_b32_e32 v169, 0xffff0000, v240
	v_lshlrev_b32_e32 v170, 16, v241
	v_and_b32_e32 v171, 0xffff0000, v241
	v_pk_add_f32 v[0:1], v[0:1], v[168:169]
	v_pk_add_f32 v[2:3], v[2:3], v[170:171]
	s_nop 0
	v_cvt_pk_bf16_f32 v24, v24, v25
	v_cvt_pk_bf16_f32 v25, v26, v27
	v_cvt_pk_bf16_f32 v26, v16, v17
	v_cvt_pk_bf16_f32 v27, v18, v19
	v_cvt_pk_bf16_f32 v8, v8, v9
	v_cvt_pk_bf16_f32 v9, v10, v11
	v_cvt_pk_bf16_f32 v10, v0, v1
	v_cvt_pk_bf16_f32 v11, v2, v3
	s_nop 1
	v_permlane16_swap_b32_e32 v24, v26
	v_permlane16_swap_b32_e32 v25, v27
	v_permlane16_swap_b32_e32 v8, v10
	v_permlane16_swap_b32_e32 v9, v11
	global_store_dwordx4 v141, v[24:27], s[26:27] offset:256
	global_store_dwordx4 v141, v[8:11], s[26:27] offset:320
	s_and_b64 s[0:1], s[56:57], s[8:9]
	s_andn2_b64 vcc, exec, s[0:1]
	s_waitcnt vmcnt(0)
	s_cbranch_vccnz .LBB0_1077
	s_barrier
	s_branch .LBB0_1077
